# lgkmcnt ladder in the 5 GEMM k-loops (counted waits per MFMA instead of lgkmcnt(0) before the first)
# speedup vs baseline: 1.0135x; 1.0135x over previous
.LBB0_161:
	s_and_b32 s22, s7, 0x18000
	v_add_u32_e32 v128, s22, v181
	v_add_u32_e32 v150, 0x2000, v128
	v_readfirstlane_b32 s22, v128
	s_waitcnt vmcnt(8)
	v_lshl_add_u64 v[148:149], v[144:145], 0, s[4:5]
	s_mov_b32 m0, s22
	v_readfirstlane_b32 s22, v150
	v_add_u32_e32 v150, 0x4000, v128
	s_waitcnt lgkmcnt(0)
	s_barrier
	global_load_lds_dwordx4 v[148:149], off
	v_lshl_add_u64 v[148:149], v[146:147], 0, s[4:5]
	s_mov_b32 m0, s22
	v_readfirstlane_b32 s22, v150
	v_add_u32_e32 v128, 0x6000, v128
	global_load_lds_dwordx4 v[148:149], off
	v_lshl_add_u64 v[148:149], v[140:141], 0, s[4:5]
	s_mov_b32 m0, s22
	v_readfirstlane_b32 s22, v128
	global_load_lds_dwordx4 v[148:149], off
	v_lshl_add_u64 v[148:149], v[142:143], 0, s[4:5]
	s_mov_b32 m0, s22
	s_add_i32 s22, s7, 0xfffe8000
	global_load_lds_dwordx4 v[148:149], off
	s_and_b32 s22, s22, 0x18000
	s_add_i32 s22, s22, 16
	v_add_u32_e32 v128, s22, v182
	v_add_u32_e32 v176, s22, v184
	v_add_u32_e32 v177, s22, v185
	v_add_u32_e32 v152, v128, v183
	v_add_u32_e32 v156, v176, v183
	v_add_u32_e32 v168, v177, v183
	v_add_u32_e32 v128, v128, v186
	ds_read_b128 v[148:151], v152
	ds_read_b128 v[152:155], v152 offset:2048
	ds_read_b128 v[156:159], v156 offset:16384
	ds_read_b128 v[160:163], v168 offset:18432
	ds_read_b128 v[164:167], v168 offset:20480
	ds_read_b128 v[168:171], v168 offset:22528
	ds_read_b128 v[172:175], v128
	ds_read_b128 v[210:213], v128 offset:2048
	v_add_u32_e32 v128, v176, v186
	v_add_u32_e32 v176, v177, v186
	ds_read_b128 v[214:217], v128 offset:16384
	ds_read_b128 v[218:221], v176 offset:18432
	ds_read_b128 v[222:225], v176 offset:20480
	ds_read_b128 v[226:229], v176 offset:22528
	s_waitcnt lgkmcnt(9)
	v_mfma_f32_32x32x16_bf16 v[112:127], v[148:151], v[156:159], v[112:127]
	s_add_u32 s4, s4, 64
	s_addc_u32 s5, s5, 0
	s_add_i32 s7, s7, 0x8000
	s_cmpk_eq_i32 s4, 0x740
	s_waitcnt lgkmcnt(8)
	v_mfma_f32_32x32x16_bf16 v[96:111], v[148:151], v[160:163], v[96:111]
	s_waitcnt lgkmcnt(7)
	v_mfma_f32_32x32x16_bf16 v[48:63], v[148:151], v[164:167], v[48:63]
	s_waitcnt lgkmcnt(6)
	v_mfma_f32_32x32x16_bf16 v[32:47], v[148:151], v[168:171], v[32:47]
	v_mfma_f32_32x32x16_bf16 v[80:95], v[152:155], v[156:159], v[80:95]
	v_mfma_f32_32x32x16_bf16 v[64:79], v[152:155], v[160:163], v[64:79]
	v_mfma_f32_32x32x16_bf16 v[16:31], v[152:155], v[164:167], v[16:31]
	v_mfma_f32_32x32x16_bf16 v[0:15], v[152:155], v[168:171], v[0:15]
	s_waitcnt lgkmcnt(3)
	v_mfma_f32_32x32x16_bf16 v[112:127], v[172:175], v[214:217], v[112:127]
	s_waitcnt lgkmcnt(2)
	v_mfma_f32_32x32x16_bf16 v[96:111], v[172:175], v[218:221], v[96:111]
	s_waitcnt lgkmcnt(1)
	v_mfma_f32_32x32x16_bf16 v[48:63], v[172:175], v[222:225], v[48:63]
	s_waitcnt lgkmcnt(0)
	v_mfma_f32_32x32x16_bf16 v[32:47], v[172:175], v[226:229], v[32:47]
	v_mfma_f32_32x32x16_bf16 v[80:95], v[210:213], v[214:217], v[80:95]
	v_mfma_f32_32x32x16_bf16 v[64:79], v[210:213], v[218:221], v[64:79]
	v_mfma_f32_32x32x16_bf16 v[16:31], v[210:213], v[222:225], v[16:31]
	v_mfma_f32_32x32x16_bf16 v[0:15], v[210:213], v[226:229], v[0:15]
	s_cbranch_scc0 .LBB0_161
	s_waitcnt vmcnt(8)
	v_add_u32_e32 v128, v196, v183
	s_waitcnt lgkmcnt(0)
	s_barrier
	ds_read_b128 v[140:143], v128 offset:32768
	ds_read_b128 v[144:147], v128 offset:34816
	v_add_u32_e32 v128, v197, v183
	v_add_u32_e32 v160, v198, v183
	ds_read_b128 v[148:151], v128 offset:49152
	ds_read_b128 v[152:155], v160 offset:51200
	ds_read_b128 v[156:159], v160 offset:53248
	ds_read_b128 v[160:163], v160 offset:55296
	v_add_u32_e32 v128, v196, v186
	ds_read_b128 v[164:167], v128 offset:32768
	ds_read_b128 v[168:171], v128 offset:34816
	v_add_u32_e32 v128, v197, v186
	v_add_u32_e32 v176, v198, v186
	ds_read_b128 v[172:175], v128 offset:49152
	ds_read_b128 v[210:213], v176 offset:51200
	ds_read_b128 v[214:217], v176 offset:53248
	ds_read_b128 v[218:221], v176 offset:55296
	s_waitcnt lgkmcnt(0)
	v_mfma_f32_32x32x16_bf16 v[112:127], v[140:143], v[148:151], v[112:127]
	s_waitcnt vmcnt(4)
	v_add_u32_e32 v128, v193, v186
	s_waitcnt lgkmcnt(0)
	s_barrier
	v_add_u32_e32 v176, v194, v183
	v_mfma_f32_32x32x16_bf16 v[96:111], v[140:143], v[152:155], v[96:111]
	v_mfma_f32_32x32x16_bf16 v[48:63], v[140:143], v[156:159], v[48:63]
	v_mfma_f32_32x32x16_bf16 v[32:47], v[140:143], v[160:163], v[32:47]
	v_mfma_f32_32x32x16_bf16 v[80:95], v[144:147], v[148:151], v[80:95]
	v_mfma_f32_32x32x16_bf16 v[64:79], v[144:147], v[152:155], v[64:79]
	v_add_u32_e32 v152, v194, v186
	v_mfma_f32_32x32x16_bf16 v[16:31], v[144:147], v[156:159], v[16:31]
	v_mfma_f32_32x32x16_bf16 v[0:15], v[144:147], v[160:163], v[0:15]
	ds_read_b128 v[140:143], v128 offset:4096
	ds_read_b128 v[144:147], v128 offset:2048
	ds_read_b128 v[148:151], v128 offset:6144
	ds_read_b128 v[152:155], v152
	v_add_u32_e32 v128, v195, v186
	ds_read_b128 v[156:159], v128 offset:2048
	ds_read_b128 v[160:163], v128
	v_add_u32_e32 v128, v193, v183
	v_mfma_f32_32x32x16_bf16 v[112:127], v[164:167], v[172:175], v[112:127]
	v_mfma_f32_32x32x16_bf16 v[96:111], v[164:167], v[210:213], v[96:111]
	v_mfma_f32_32x32x16_bf16 v[48:63], v[164:167], v[214:217], v[48:63]
	v_mfma_f32_32x32x16_bf16 v[32:47], v[164:167], v[218:221], v[32:47]
	v_mfma_f32_32x32x16_bf16 v[80:95], v[168:171], v[172:175], v[80:95]
	ds_read_b128 v[164:167], v128 offset:4096
	ds_read_b128 v[172:175], v128 offset:2048
	v_mfma_f32_32x32x16_bf16 v[64:79], v[168:171], v[210:213], v[64:79]
	v_mfma_f32_32x32x16_bf16 v[16:31], v[168:171], v[214:217], v[16:31]
	ds_read_b128 v[210:213], v128 offset:6144
	ds_read_b128 v[214:217], v176
	v_add_u32_e32 v128, v195, v183
	ds_read_b128 v[222:225], v128 offset:2048
	ds_read_b128 v[226:229], v128
	v_mfma_f32_32x32x16_bf16 v[0:15], v[168:171], v[218:221], v[0:15]
	s_waitcnt lgkmcnt(0)
	v_mfma_f32_32x32x16_bf16 v[112:127], v[226:229], v[214:217], v[112:127]
	s_waitcnt vmcnt(0)
	v_add_u32_e32 v128, v187, v186
	s_waitcnt lgkmcnt(0)
	s_barrier
	v_add_u32_e32 v176, v188, v183
	v_mfma_f32_32x32x16_bf16 v[96:111], v[226:229], v[172:175], v[96:111]
	v_mfma_f32_32x32x16_bf16 v[48:63], v[226:229], v[164:167], v[48:63]
	v_mfma_f32_32x32x16_bf16 v[32:47], v[226:229], v[210:213], v[32:47]
	v_mfma_f32_32x32x16_bf16 v[80:95], v[222:225], v[214:217], v[80:95]
	v_mfma_f32_32x32x16_bf16 v[64:79], v[222:225], v[172:175], v[64:79]
	v_mfma_f32_32x32x16_bf16 v[16:31], v[222:225], v[164:167], v[16:31]
	v_add_u32_e32 v164, v188, v186
	v_mfma_f32_32x32x16_bf16 v[0:15], v[222:225], v[210:213], v[0:15]
	v_mfma_f32_32x32x16_bf16 v[112:127], v[160:163], v[152:155], v[112:127]
	v_mfma_f32_32x32x16_bf16 v[96:111], v[160:163], v[144:147], v[96:111]
	v_mfma_f32_32x32x16_bf16 v[48:63], v[160:163], v[140:143], v[48:63]
	v_mfma_f32_32x32x16_bf16 v[32:47], v[160:163], v[148:151], v[32:47]
	v_mfma_f32_32x32x16_bf16 v[80:95], v[156:159], v[152:155], v[80:95]
	ds_read_b128 v[152:155], v128 offset:4096
	ds_read_b128 v[160:163], v128 offset:2048
	v_mfma_f32_32x32x16_bf16 v[64:79], v[156:159], v[144:147], v[64:79]
	ds_read_b128 v[144:147], v128 offset:6144
	ds_read_b128 v[164:167], v164
	v_add_u32_e32 v128, v189, v186
	ds_read_b128 v[168:171], v128 offset:2048
	ds_read_b128 v[172:175], v128
	v_add_u32_e32 v128, v187, v183
	v_mfma_f32_32x32x16_bf16 v[16:31], v[156:159], v[140:143], v[16:31]
	ds_read_b128 v[140:143], v128 offset:4096
	ds_read_b128 v[210:213], v128 offset:2048
	ds_read_b128 v[214:217], v128 offset:6144
	ds_read_b128 v[218:221], v176
	v_add_u32_e32 v128, v189, v183
	ds_read_b128 v[222:225], v128 offset:2048
	ds_read_b128 v[226:229], v128
	v_mfma_f32_32x32x16_bf16 v[0:15], v[156:159], v[148:151], v[0:15]
	s_waitcnt lgkmcnt(0)
	v_mfma_f32_32x32x16_bf16 v[112:127], v[226:229], v[218:221], v[112:127]
	s_waitcnt lgkmcnt(0)
	s_cmp_eq_u32 s94, 6
	s_cselect_b64 s[24:25], -1, 0
	s_cmp_lg_u32 s94, 6
	s_barrier
	s_cselect_b64 s[22:23], -1, 0
	s_mov_b64 s[58:59], -1
	v_mfma_f32_32x32x16_bf16 v[96:111], v[226:229], v[210:213], v[96:111]
	v_mfma_f32_32x32x16_bf16 v[48:63], v[226:229], v[140:143], v[48:63]
	v_mfma_f32_32x32x16_bf16 v[32:47], v[226:229], v[214:217], v[32:47]
	v_mfma_f32_32x32x16_bf16 v[80:95], v[222:225], v[218:221], v[80:95]
	v_mfma_f32_32x32x16_bf16 v[64:79], v[222:225], v[210:213], v[64:79]
	v_mov_b32_e32 v211, v133
	s_nop 0
	v_and_b32_e32 v212, 31, v211
	v_ashrrev_i32_e32 v213, 5, v211
	v_mfma_f32_32x32x16_bf16 v[16:31], v[222:225], v[140:143], v[16:31]
	v_add_u32_e32 v140, s6, v190
	v_or_b32_e32 v142, s93, v132
	v_ashrrev_i32_e32 v210, 14, v140
	v_cmp_lt_i32_e64 s[4:5], s55, v142
	v_mfma_f32_32x32x16_bf16 v[0:15], v[222:225], v[214:217], v[0:15]
	v_mfma_f32_32x32x16_bf16 v[112:127], v[172:175], v[164:167], v[112:127]
	v_mfma_f32_32x32x16_bf16 v[96:111], v[172:175], v[160:163], v[96:111]
	v_mfma_f32_32x32x16_bf16 v[48:63], v[172:175], v[152:155], v[48:63]
	v_mfma_f32_32x32x16_bf16 v[32:47], v[172:175], v[144:147], v[32:47]
	v_mfma_f32_32x32x16_bf16 v[80:95], v[168:171], v[164:167], v[80:95]
	v_mfma_f32_32x32x16_bf16 v[64:79], v[168:171], v[160:163], v[64:79]
	v_mfma_f32_32x32x16_bf16 v[16:31], v[168:171], v[152:155], v[16:31]
	v_mfma_f32_32x32x16_bf16 v[0:15], v[168:171], v[144:147], v[0:15]
	s_and_saveexec_b64 s[48:49], s[4:5]
	s_cbranch_execz .LBB0_197
	s_cmp_lt_i32 s94, 8
	s_cbranch_scc1 .LBB0_165
	s_cmp_lg_u32 s94, 8
	s_mov_b64 s[6:7], -1
	s_cselect_b64 s[58:59], -1, 0
	s_cbranch_execz .LBB0_166
	s_branch .LBB0_167

.LBB0_303:
	s_and_b32 s24, s16, 0x18000
	v_add_u32_e32 v129, s24, v137
	s_lshr_b32 s24, s17, 1
	v_add_u32_e32 v160, s24, v128
	v_ashrrev_i32_e32 v161, 31, v160
	v_lshlrev_b64 v[160:161], 9, v[160:161]
	v_and_or_b32 v131, s6, 32, v140
	v_lshl_add_u64 v[160:161], v[132:133], 0, v[160:161]
	v_lshlrev_b32_e32 v144, 1, v131
	v_readfirstlane_b32 s25, v129
	s_waitcnt vmcnt(8)
	v_lshl_add_u64 v[160:161], v[160:161], 0, v[144:145]
	s_mov_b32 m0, s25
	s_waitcnt lgkmcnt(0)
	s_barrier
	global_load_lds_dwordx4 v[160:161], off
	v_add_u32_e32 v160, s24, v130
	v_ashrrev_i32_e32 v161, 31, v160
	v_lshlrev_b64 v[160:161], 9, v[160:161]
	v_add_u32_e32 v131, 0x2000, v129
	v_lshl_add_u64 v[160:161], v[134:135], 0, v[160:161]
	v_readfirstlane_b32 s24, v131
	v_add_u32_e32 v131, 0x4000, v129
	v_lshl_add_u64 v[160:161], v[160:161], 0, v[144:145]
	s_mov_b32 m0, s24
	v_readfirstlane_b32 s24, v131
	v_add_u32_e32 v129, 0x6000, v129
	global_load_lds_dwordx4 v[160:161], off
	s_mov_b32 m0, s24
	v_readfirstlane_b32 s24, v129
	global_load_lds_dwordx4 v[156:157], off
	s_mov_b32 m0, s24
	s_add_i32 s24, s16, 0xfffe8000
	global_load_lds_dwordx4 v[158:159], off
	s_and_b32 s24, s24, 0x18000
	s_add_i32 s24, s24, 16
	v_add_u32_e32 v129, s24, v139
	v_add_u32_e32 v131, v129, v149
	ds_read_b128 v[192:195], v131
	ds_read_b128 v[196:199], v131 offset:2048
	v_add_u32_e32 v131, s24, v162
	v_add_u32_e32 v144, v131, v149
	v_add_u32_e32 v160, s24, v163
	v_add_u32_e32 v129, v129, v164
	v_add_u32_e32 v161, v160, v149
	ds_read_b128 v[200:203], v144 offset:16384
	ds_read_b128 v[204:207], v161 offset:18432
	ds_read_b128 v[208:211], v161 offset:20480
	ds_read_b128 v[212:215], v161 offset:22528
	ds_read_b128 v[216:219], v129
	ds_read_b128 v[220:223], v129 offset:2048
	v_add_u32_e32 v129, v131, v164
	v_add_u32_e32 v131, v160, v164
	ds_read_b128 v[224:227], v129 offset:16384
	ds_read_b128 v[228:231], v131 offset:18432
	ds_read_b128 v[232:235], v131 offset:20480
	ds_read_b128 v[236:239], v131 offset:22528
	s_waitcnt lgkmcnt(9)
	v_mfma_f32_32x32x16_bf16 v[112:127], v[192:195], v[200:203], v[112:127]
	s_add_i32 s17, s17, 1
	s_add_i32 s6, s6, 32
	s_add_i32 s16, s16, 0x8000
	v_lshl_add_u64 v[156:157], v[156:157], 0, 64
	v_lshl_add_u64 v[158:159], v[158:159], 0, 64
	s_cmp_lg_u32 s16, 0x200000
	s_waitcnt lgkmcnt(8)
	v_mfma_f32_32x32x16_bf16 v[96:111], v[192:195], v[204:207], v[96:111]
	s_waitcnt lgkmcnt(7)
	v_mfma_f32_32x32x16_bf16 v[48:63], v[192:195], v[208:211], v[48:63]
	s_waitcnt lgkmcnt(6)
	v_mfma_f32_32x32x16_bf16 v[32:47], v[192:195], v[212:215], v[32:47]
	v_mfma_f32_32x32x16_bf16 v[80:95], v[196:199], v[200:203], v[80:95]
	v_mfma_f32_32x32x16_bf16 v[64:79], v[196:199], v[204:207], v[64:79]
	v_mfma_f32_32x32x16_bf16 v[16:31], v[196:199], v[208:211], v[16:31]
	v_mfma_f32_32x32x16_bf16 v[0:15], v[196:199], v[212:215], v[0:15]
	s_waitcnt lgkmcnt(3)
	v_mfma_f32_32x32x16_bf16 v[112:127], v[216:219], v[224:227], v[112:127]
	s_waitcnt lgkmcnt(2)
	v_mfma_f32_32x32x16_bf16 v[96:111], v[216:219], v[228:231], v[96:111]
	s_waitcnt lgkmcnt(1)
	v_mfma_f32_32x32x16_bf16 v[48:63], v[216:219], v[232:235], v[48:63]
	s_waitcnt lgkmcnt(0)
	v_mfma_f32_32x32x16_bf16 v[32:47], v[216:219], v[236:239], v[32:47]
	v_mfma_f32_32x32x16_bf16 v[80:95], v[220:223], v[224:227], v[80:95]
	v_mfma_f32_32x32x16_bf16 v[64:79], v[220:223], v[228:231], v[64:79]
	v_mfma_f32_32x32x16_bf16 v[16:31], v[220:223], v[232:235], v[16:31]
	v_mfma_f32_32x32x16_bf16 v[0:15], v[220:223], v[236:239], v[0:15]
	s_cbranch_scc1 .LBB0_303
	s_waitcnt vmcnt(8)
	v_add_u32_e32 v132, v174, v149
	v_add_u32_e32 v144, v175, v149
	s_waitcnt lgkmcnt(0)
	s_barrier
	ds_read_b128 v[128:131], v132 offset:32768
	ds_read_b128 v[132:135], v132 offset:34816
	v_add_u32_e32 v160, v176, v149
	ds_read_b128 v[156:159], v144 offset:49152
	ds_read_b128 v[192:195], v160 offset:51200
	ds_read_b128 v[196:199], v160 offset:53248
	ds_read_b128 v[200:203], v160 offset:55296
	v_add_u32_e32 v144, v174, v164
	ds_read_b128 v[204:207], v144 offset:32768
	ds_read_b128 v[208:211], v144 offset:34816
	v_add_u32_e32 v144, v175, v164
	v_add_u32_e32 v160, v176, v164
	ds_read_b128 v[212:215], v144 offset:49152
	ds_read_b128 v[216:219], v160 offset:51200
	ds_read_b128 v[220:223], v160 offset:53248
	ds_read_b128 v[224:227], v160 offset:55296
	s_waitcnt lgkmcnt(0)
	v_mfma_f32_32x32x16_bf16 v[112:127], v[128:131], v[156:159], v[112:127]
	s_waitcnt vmcnt(4)
	v_add_u32_e32 v144, v173, v164
	s_waitcnt lgkmcnt(0)
	s_barrier
	v_add_u32_e32 v160, v172, v149
	v_mfma_f32_32x32x16_bf16 v[96:111], v[128:131], v[192:195], v[96:111]
	v_mfma_f32_32x32x16_bf16 v[48:63], v[128:131], v[196:199], v[48:63]
	v_mfma_f32_32x32x16_bf16 v[32:47], v[128:131], v[200:203], v[32:47]
	v_mfma_f32_32x32x16_bf16 v[80:95], v[132:135], v[156:159], v[80:95]
	v_mfma_f32_32x32x16_bf16 v[64:79], v[132:135], v[192:195], v[64:79]
	v_mfma_f32_32x32x16_bf16 v[16:31], v[132:135], v[196:199], v[16:31]
	v_mfma_f32_32x32x16_bf16 v[0:15], v[132:135], v[200:203], v[0:15]
	v_add_u32_e32 v132, v171, v164
	v_add_u32_e32 v133, v172, v164
	ds_read_b128 v[156:159], v132 offset:4096
	ds_read_b128 v[128:131], v132 offset:2048
	ds_read_b128 v[192:195], v132 offset:6144
	ds_read_b128 v[132:135], v133
	ds_read_b128 v[196:199], v144 offset:2048
	ds_read_b128 v[200:203], v144
	v_add_u32_e32 v144, v171, v149
	v_mfma_f32_32x32x16_bf16 v[112:127], v[204:207], v[212:215], v[112:127]
	v_mfma_f32_32x32x16_bf16 v[96:111], v[204:207], v[216:219], v[96:111]
	v_mfma_f32_32x32x16_bf16 v[48:63], v[204:207], v[220:223], v[48:63]
	v_mfma_f32_32x32x16_bf16 v[32:47], v[204:207], v[224:227], v[32:47]
	v_mfma_f32_32x32x16_bf16 v[80:95], v[208:211], v[212:215], v[80:95]
	ds_read_b128 v[204:207], v144 offset:4096
	ds_read_b128 v[212:215], v144 offset:2048
	v_mfma_f32_32x32x16_bf16 v[64:79], v[208:211], v[216:219], v[64:79]
	v_mfma_f32_32x32x16_bf16 v[16:31], v[208:211], v[220:223], v[16:31]
	ds_read_b128 v[216:219], v144 offset:6144
	ds_read_b128 v[220:223], v160
	v_add_u32_e32 v144, v173, v149
	ds_read_b128 v[228:231], v144 offset:2048
	ds_read_b128 v[232:235], v144
	v_mfma_f32_32x32x16_bf16 v[0:15], v[208:211], v[224:227], v[0:15]
	s_waitcnt lgkmcnt(0)
	v_mfma_f32_32x32x16_bf16 v[112:127], v[232:235], v[220:223], v[112:127]
	s_waitcnt vmcnt(0)
	v_add_u32_e32 v144, v167, v164
	s_waitcnt lgkmcnt(0)
	s_barrier
	s_ashr_i32 s16, s22, 5
	v_mfma_f32_32x32x16_bf16 v[80:95], v[228:231], v[220:223], v[80:95]
	v_mfma_f32_32x32x16_bf16 v[96:111], v[232:235], v[212:215], v[96:111]
	v_mfma_f32_32x32x16_bf16 v[48:63], v[232:235], v[204:207], v[48:63]
	v_mfma_f32_32x32x16_bf16 v[32:47], v[232:235], v[216:219], v[32:47]
	v_mfma_f32_32x32x16_bf16 v[64:79], v[228:231], v[212:215], v[64:79]
	v_mfma_f32_32x32x16_bf16 v[16:31], v[228:231], v[204:207], v[16:31]
	v_mfma_f32_32x32x16_bf16 v[0:15], v[228:231], v[216:219], v[0:15]
	v_mfma_f32_32x32x16_bf16 v[112:127], v[200:203], v[132:135], v[112:127]
	v_mfma_f32_32x32x16_bf16 v[80:95], v[196:199], v[132:135], v[80:95]
	v_add_u32_e32 v132, v165, v164
	v_add_u32_e32 v133, v166, v164
	v_mfma_f32_32x32x16_bf16 v[96:111], v[200:203], v[128:131], v[96:111]
	v_mfma_f32_32x32x16_bf16 v[48:63], v[200:203], v[156:159], v[48:63]
	v_mfma_f32_32x32x16_bf16 v[32:47], v[200:203], v[192:195], v[32:47]
	ds_read_b128 v[200:203], v132 offset:4096
	ds_read_b128 v[204:207], v132 offset:2048
	v_mfma_f32_32x32x16_bf16 v[64:79], v[196:199], v[128:131], v[64:79]
	ds_read_b128 v[128:131], v132 offset:6144
	ds_read_b128 v[208:211], v133
	ds_read_b128 v[132:135], v144 offset:2048
	ds_read_b128 v[212:215], v144
	v_add_u32_e32 v144, v165, v149
	ds_read_b128 v[216:219], v144 offset:4096
	ds_read_b128 v[220:223], v144 offset:2048
	v_mfma_f32_32x32x16_bf16 v[16:31], v[196:199], v[156:159], v[16:31]
	v_add_u32_e32 v156, v166, v149
	ds_read_b128 v[224:227], v144 offset:6144
	ds_read_b128 v[228:231], v156
	v_add_u32_e32 v144, v167, v149
	ds_read_b128 v[232:235], v144 offset:2048
	ds_read_b128 v[236:239], v144
	v_mfma_f32_32x32x16_bf16 v[0:15], v[196:199], v[192:195], v[0:15]
	v_mov_b32_e32 v159, v141
	s_waitcnt lgkmcnt(0)
	s_barrier
	s_lshl_b32 s6, s16, 8
	v_and_b32_e32 v144, 31, v159
	v_or3_b32 v156, v148, v144, s6
	v_ashrrev_i32_e32 v157, 31, v156
	v_lshl_add_u64 v[156:157], v[156:157], 2, s[12:13]
	global_load_dword v160, v[156:157], off
	global_load_dword v161, v[156:157], off offset:128
	s_waitcnt lgkmcnt(0)
	v_mfma_f32_32x32x16_bf16 v[112:127], v[236:239], v[228:231], v[112:127]
	s_ashr_i32 s17, s16, 31
	v_add_u32_e32 v156, s23, v168
	s_lshl_b64 s[16:17], s[16:17], 22
	v_ashrrev_i32_e32 v157, 31, v156
	s_add_u32 s16, s4, s16
	s_addc_u32 s17, s5, s17
	v_lshlrev_b64 v[156:157], 9, v[156:157]
	v_mfma_f32_32x32x16_bf16 v[96:111], v[236:239], v[220:223], v[96:111]
	v_lshl_add_u64 v[156:157], s[16:17], 0, v[156:157]
	v_lshlrev_b32_e32 v144, 1, v148
	v_lshl_add_u64 v[156:157], v[156:157], 0, v[144:145]
	v_ashrrev_i32_e32 v158, 3, v159
	v_and_b32_e32 v144, -4, v158
	v_lshrrev_b32_e32 v190, 3, v159
	v_mfma_f32_32x32x16_bf16 v[112:127], v[212:215], v[208:211], v[112:127]
	v_lshlrev_b32_e32 v192, 7, v144
	v_bfi_b32 v194, 3, v190, v158
	v_lshl_add_u32 v192, v194, 4, v192
	v_lshlrev_b32_e32 v194, 1, v159
	v_bfe_u32 v193, v159, 3, 2
	v_bitop3_b32 v195, v144, v193, 1 bitop3:0x36
	v_bitop3_b32 v190, v190, v158, 3 bitop3:0x4e
	v_mfma_f32_32x32x16_bf16 v[96:111], v[212:215], v[204:207], v[96:111]
	s_add_i32 s22, s22, s86
	s_cmp_gt_i32 s22, 63
	v_mfma_f32_32x32x16_bf16 v[48:63], v[236:239], v[216:219], v[48:63]
	v_mfma_f32_32x32x16_bf16 v[16:31], v[232:235], v[216:219], v[16:31]
	v_and_b32_e32 v216, 14, v194
	v_or_b32_e32 v194, 1, v144
	v_lshlrev_b32_e32 v194, 7, v194
	v_lshl_add_u32 v194, v195, 4, v194
	v_or_b32_e32 v195, 2, v144
	v_lshlrev_b32_e32 v195, 7, v195
	v_bitop3_b32 v144, v144, v193, 2 bitop3:0x36
	v_or_b32_e32 v193, 3, v158
	v_lshl_add_u32 v217, v144, 4, v195
	v_lshlrev_b32_e32 v144, 7, v193
	v_lshl_add_u32 v218, v190, 4, v144
	v_or_b32_e32 v190, v192, v216
	v_mov_b32_e32 v192, v112
	v_mov_b32_e32 v193, v96
	v_or_b32_e32 v194, v194, v216
	v_mov_b32_e32 v96, v113
	v_add_u32_e32 v112, v169, v194
	v_xad_u32 v113, v194, 64, v169
	v_mov_b32_e32 v194, v114
	v_mov_b32_e32 v195, v98
	v_mfma_f32_32x32x16_bf16 v[32:47], v[236:239], v[224:227], v[32:47]
	v_add_u32_e32 v144, v169, v190
	v_xad_u32 v190, v190, 64, v169
	s_waitcnt vmcnt(0)
	v_add_f32_e64 v192, v192, v160
	v_add_f32_e64 v193, v193, v161
	v_pk_add_f32 v[96:97], v[96:97], v[160:161]
	v_mul_f32_e32 v98, 0xbfb8aa3b, v192
	v_mul_f32_e32 v114, 0xbfb8aa3b, v193
	v_pk_add_f32 v[194:195], v[194:195], v[160:161]
	v_mul_f32_e32 v196, 0xbfb8aa3b, v96
	v_mul_f32_e32 v197, 0xbfb8aa3b, v97
	v_exp_f32_e32 v98, v98
	v_exp_f32_e32 v114, v114
	v_mul_f32_e32 v198, 0xbfb8aa3b, v194
	v_mul_f32_e32 v199, 0xbfb8aa3b, v195
	v_exp_f32_e32 v196, v196
	v_exp_f32_e32 v197, v197
	v_exp_f32_e32 v198, v198
	v_exp_f32_e32 v199, v199
	v_add_f32_e32 v98, 1.0, v98
	v_add_f32_e32 v114, 1.0, v114
	v_mfma_f32_32x32x16_bf16 v[64:79], v[232:235], v[220:223], v[64:79]
	v_add_f32_e32 v219, 1.0, v196
	v_add_f32_e32 v220, 1.0, v197
	v_rcp_f32_e32 v196, v98
	v_rcp_f32_e32 v197, v114
	v_add_f32_e32 v221, 1.0, v198
	v_add_f32_e32 v222, 1.0, v199
	v_rcp_f32_e32 v198, v219
	v_rcp_f32_e32 v199, v220
	v_mfma_f32_32x32x16_bf16 v[48:63], v[212:215], v[200:203], v[48:63]
	v_mul_f32_e64 v192, v192, v196
	v_mul_f32_e64 v193, v193, v197
	v_mul_f32_e64 v96, v96, v198
	v_mul_f32_e64 v97, v97, v199
	v_cvt_pk_bf16_f32 v98, v192, v193
	v_cvt_pk_bf16_f32 v96, v96, v97
	ds_write_b16 v144, v98
	ds_write_b16_d16_hi v190, v98
	ds_write_b16 v112, v96
	ds_write_b16_d16_hi v113, v96
	v_mov_b32_e32 v98, v115
	v_mfma_f32_32x32x16_bf16 v[32:47], v[212:215], v[128:131], v[32:47]
	v_rcp_f32_e32 v212, v221
	v_rcp_f32_e32 v213, v222
	v_pk_add_f32 v[98:99], v[98:99], v[160:161]
	v_pk_mul_f32 v[96:97], v[194:195], v[212:213]
	s_nop 0
	v_cvt_pk_bf16_f32 v192, v96, v97
	v_mul_f32_e32 v96, 0xbfb8aa3b, v98
	v_exp_f32_e32 v114, v96
	v_mul_f32_e32 v96, 0xbfb8aa3b, v99
	v_exp_f32_e32 v115, v96
	v_or_b32_e32 v97, v217, v216
	v_add_f32_e32 v114, 1.0, v114
	v_rcp_f32_e32 v114, v114
	v_add_f32_e32 v115, 1.0, v115
	v_rcp_f32_e32 v115, v115
	v_add_u32_e32 v96, v169, v97
	v_xad_u32 v97, v97, 64, v169
	ds_write_b16 v96, v192
	v_pk_mul_f32 v[98:99], v[98:99], v[114:115]
	ds_write_b16_d16_hi v97, v192
	v_cvt_pk_bf16_f32 v114, v98, v99
	v_or_b32_e32 v99, v218, v216
	v_add_u32_e32 v98, v169, v99
	v_xad_u32 v99, v99, 64, v169
	ds_write_b16 v98, v114
	ds_write_b16_d16_hi v99, v114
	v_mov_b32_e32 v114, v116
	v_mov_b32_e32 v115, v100
	v_pk_add_f32 v[114:115], v[114:115], v[160:161]
	v_mfma_f32_32x32x16_bf16 v[80:95], v[232:235], v[228:231], v[80:95]
	v_mul_f32_e32 v100, 0xbfb8aa3b, v114
	v_exp_f32_e32 v100, v100
	v_mul_f32_e32 v116, 0xbfb8aa3b, v115
	v_exp_f32_e32 v116, v116
	v_add_f32_e32 v100, 1.0, v100
	v_rcp_f32_e32 v192, v100
	v_add_f32_e32 v100, 1.0, v116
	v_rcp_f32_e32 v193, v100
	v_mov_b32_e32 v100, v117
	v_pk_add_f32 v[100:101], v[100:101], v[160:161]
	v_mfma_f32_32x32x16_bf16 v[80:95], v[132:135], v[208:211], v[80:95]
	v_mul_f32_e32 v116, 0xbfb8aa3b, v100
	v_mul_f32_e32 v117, 0xbfb8aa3b, v101
	v_exp_f32_e32 v116, v116
	v_exp_f32_e32 v117, v117
	v_pk_mul_f32 v[114:115], v[114:115], v[192:193]
	v_add_f32_e32 v116, 1.0, v116
	v_add_f32_e32 v117, 1.0, v117
	v_rcp_f32_e32 v116, v116
	v_rcp_f32_e32 v117, v117
	v_cvt_pk_bf16_f32 v114, v114, v115
	ds_write_b16 v144, v114 offset:1024
	ds_write_b16_d16_hi v190, v114 offset:1024
	v_mfma_f32_32x32x16_bf16 v[64:79], v[132:135], v[204:207], v[64:79]
	v_mul_f32_e64 v100, v100, v116
	v_mul_f32_e64 v101, v101, v117
	v_cvt_pk_bf16_f32 v100, v100, v101
	ds_write_b16 v112, v100 offset:1024
	ds_write_b16_d16_hi v113, v100 offset:1024
	v_mov_b32_e32 v100, v118
	v_mov_b32_e32 v101, v102
	v_pk_add_f32 v[100:101], v[100:101], v[160:161]
	v_mfma_f32_32x32x16_bf16 v[0:15], v[232:235], v[224:227], v[0:15]
	v_mul_f32_e32 v102, 0xbfb8aa3b, v100
	v_exp_f32_e32 v102, v102
	v_mul_f32_e32 v114, 0xbfb8aa3b, v101
	v_exp_f32_e32 v115, v114
	v_add_f32_e32 v102, 1.0, v102
	v_rcp_f32_e32 v114, v102
	v_add_f32_e32 v102, 1.0, v115
	v_rcp_f32_e32 v115, v102
	v_mov_b32_e32 v102, v119
	v_pk_add_f32 v[102:103], v[102:103], v[160:161]
	v_mfma_f32_32x32x16_bf16 v[16:31], v[132:135], v[200:203], v[16:31]
	v_mul_f32_e32 v116, 0xbfb8aa3b, v102
	v_mul_f32_e32 v117, 0xbfb8aa3b, v103
	v_exp_f32_e32 v116, v116
	v_exp_f32_e32 v117, v117
	v_pk_mul_f32 v[100:101], v[100:101], v[114:115]
	v_add_f32_e32 v114, 1.0, v116
	v_add_f32_e32 v115, 1.0, v117
	v_rcp_f32_e32 v114, v114
	v_rcp_f32_e32 v115, v115
	v_cvt_pk_bf16_f32 v100, v100, v101
	ds_write_b16 v96, v100 offset:1024
	ds_write_b16_d16_hi v97, v100 offset:1024
	v_mfma_f32_32x32x16_bf16 v[0:15], v[132:135], v[128:131], v[0:15]
	v_mul_f32_e64 v100, v102, v114
	v_mul_f32_e64 v101, v103, v115
	v_cvt_pk_bf16_f32 v100, v100, v101
	ds_write_b16 v98, v100 offset:1024
	ds_write_b16_d16_hi v99, v100 offset:1024
	v_mov_b32_e32 v100, v120
	v_mov_b32_e32 v101, v104
	v_pk_add_f32 v[100:101], v[100:101], v[160:161]
	v_mov_b32_e32 v104, v121
	v_mul_f32_e32 v102, 0xbfb8aa3b, v100
	v_mul_f32_e32 v103, 0xbfb8aa3b, v101
	v_exp_f32_e32 v102, v102
	v_exp_f32_e32 v103, v103
	v_pk_add_f32 v[104:105], v[104:105], v[160:161]
	v_add_f32_e32 v102, 1.0, v102
	v_add_f32_e32 v103, 1.0, v103
	v_mul_f32_e32 v114, 0xbfb8aa3b, v104
	v_mul_f32_e32 v115, 0xbfb8aa3b, v105
	v_rcp_f32_e32 v102, v102
	v_rcp_f32_e32 v103, v103
	v_exp_f32_e32 v114, v114
	v_exp_f32_e32 v115, v115
	v_pk_mul_f32 v[100:101], v[100:101], v[102:103]
	v_add_f32_e32 v102, 1.0, v114
	v_add_f32_e32 v103, 1.0, v115
	v_rcp_f32_e32 v102, v102
	v_rcp_f32_e32 v103, v103
	v_cvt_pk_bf16_f32 v100, v100, v101
	ds_write_b16 v144, v100 offset:2048
	ds_write_b16_d16_hi v190, v100 offset:2048
	v_pk_mul_f32 v[100:101], v[104:105], v[102:103]
	s_nop 0
	v_cvt_pk_bf16_f32 v100, v100, v101
	ds_write_b16 v112, v100 offset:2048
	ds_write_b16_d16_hi v113, v100 offset:2048
	v_mov_b32_e32 v100, v122
	v_mov_b32_e32 v101, v106
	v_pk_add_f32 v[100:101], v[100:101], v[160:161]
	v_mov_b32_e32 v106, v123
	v_mul_f32_e32 v102, 0xbfb8aa3b, v100
	v_mul_f32_e32 v103, 0xbfb8aa3b, v101
	v_exp_f32_e32 v102, v102
	v_exp_f32_e32 v103, v103
	v_pk_add_f32 v[104:105], v[106:107], v[160:161]
	v_add_f32_e32 v102, 1.0, v102
	v_add_f32_e32 v103, 1.0, v103
	v_mul_f32_e32 v106, 0xbfb8aa3b, v104
	v_mul_f32_e32 v107, 0xbfb8aa3b, v105
	v_rcp_f32_e32 v102, v102
	v_rcp_f32_e32 v103, v103
	v_exp_f32_e32 v106, v106
	v_exp_f32_e32 v107, v107
	v_pk_mul_f32 v[100:101], v[100:101], v[102:103]
	v_add_f32_e32 v102, 1.0, v106
	v_add_f32_e32 v103, 1.0, v107
	v_rcp_f32_e32 v102, v102
	v_rcp_f32_e32 v103, v103
	v_cvt_pk_bf16_f32 v100, v100, v101
	ds_write_b16 v96, v100 offset:2048
	ds_write_b16_d16_hi v97, v100 offset:2048
	v_pk_mul_f32 v[100:101], v[104:105], v[102:103]
	s_nop 0
	v_cvt_pk_bf16_f32 v100, v100, v101
	ds_write_b16 v98, v100 offset:2048
	ds_write_b16_d16_hi v99, v100 offset:2048
	v_mov_b32_e32 v100, v124
	v_mov_b32_e32 v101, v108
	v_pk_add_f32 v[100:101], v[100:101], v[160:161]
	v_mov_b32_e32 v108, v125
	v_mul_f32_e32 v102, 0xbfb8aa3b, v100
	v_mul_f32_e32 v103, 0xbfb8aa3b, v101
	v_exp_f32_e32 v102, v102
	v_exp_f32_e32 v103, v103
	v_pk_add_f32 v[104:105], v[108:109], v[160:161]
	v_add_f32_e32 v102, 1.0, v102
	v_add_f32_e32 v103, 1.0, v103
	v_mul_f32_e32 v106, 0xbfb8aa3b, v104
	v_mul_f32_e32 v107, 0xbfb8aa3b, v105
	v_rcp_f32_e32 v102, v102
	v_rcp_f32_e32 v103, v103
	v_exp_f32_e32 v106, v106
	v_exp_f32_e32 v107, v107
	v_pk_mul_f32 v[100:101], v[100:101], v[102:103]
	v_add_f32_e32 v102, 1.0, v106
	v_add_f32_e32 v103, 1.0, v107
	v_rcp_f32_e32 v102, v102
	v_rcp_f32_e32 v103, v103
	v_cvt_pk_bf16_f32 v100, v100, v101
	ds_write_b16 v144, v100 offset:3072
	ds_write_b16_d16_hi v190, v100 offset:3072
	v_pk_mul_f32 v[100:101], v[104:105], v[102:103]
	s_nop 0
	v_cvt_pk_bf16_f32 v100, v100, v101
	ds_write_b16 v112, v100 offset:3072
	ds_write_b16_d16_hi v113, v100 offset:3072
	v_mov_b32_e32 v100, v126
	v_mov_b32_e32 v101, v110
	v_pk_add_f32 v[100:101], v[100:101], v[160:161]
	v_mov_b32_e32 v110, v127
	v_mul_f32_e32 v102, 0xbfb8aa3b, v100
	v_mul_f32_e32 v103, 0xbfb8aa3b, v101
	v_exp_f32_e32 v102, v102
	v_exp_f32_e32 v103, v103
	v_pk_add_f32 v[104:105], v[110:111], v[160:161]
	v_add_f32_e32 v102, 1.0, v102
	v_add_f32_e32 v103, 1.0, v103
	v_mul_f32_e32 v106, 0xbfb8aa3b, v104
	v_mul_f32_e32 v107, 0xbfb8aa3b, v105
	v_rcp_f32_e32 v102, v102
	v_rcp_f32_e32 v103, v103
	v_exp_f32_e32 v106, v106
	v_exp_f32_e32 v107, v107
	v_pk_mul_f32 v[100:101], v[100:101], v[102:103]
	v_add_f32_e32 v102, 1.0, v106
	v_add_f32_e32 v103, 1.0, v107
	v_rcp_f32_e32 v102, v102
	v_rcp_f32_e32 v103, v103
	v_cvt_pk_bf16_f32 v100, v100, v101
	ds_write_b16 v96, v100 offset:3072
	ds_write_b16_d16_hi v97, v100 offset:3072
	v_pk_mul_f32 v[100:101], v[104:105], v[102:103]
	s_nop 0
	v_cvt_pk_bf16_f32 v100, v100, v101
	ds_write_b16 v98, v100 offset:3072
	ds_write_b16_d16_hi v99, v100 offset:3072
	v_mov_b32_e32 v100, v80
	v_mov_b32_e32 v101, v64
	v_pk_add_f32 v[100:101], v[100:101], v[160:161]
	s_nop 0
	v_mul_f32_e32 v64, 0xbfb8aa3b, v100
	v_exp_f32_e32 v64, v64
	v_mul_f32_e32 v80, 0xbfb8aa3b, v101
	v_exp_f32_e32 v80, v80
	v_add_f32_e32 v64, 1.0, v64
	v_rcp_f32_e32 v102, v64
	v_add_f32_e32 v64, 1.0, v80
	v_rcp_f32_e32 v103, v64
	v_mov_b32_e32 v64, v81
	v_pk_add_f32 v[64:65], v[64:65], v[160:161]
	s_nop 0
	v_mul_f32_e32 v80, 0xbfb8aa3b, v64
	v_exp_f32_e32 v104, v80
	v_mul_f32_e32 v80, 0xbfb8aa3b, v65
	v_exp_f32_e32 v105, v80
	v_pk_mul_f32 v[80:81], v[100:101], v[102:103]
	v_add_f32_e32 v100, 1.0, v104
	v_rcp_f32_e32 v100, v100
	v_add_f32_e32 v101, 1.0, v105
	v_rcp_f32_e32 v101, v101
	v_cvt_pk_bf16_f32 v80, v80, v81
	ds_write_b16 v144, v80 offset:4096
	ds_write_b16_d16_hi v190, v80 offset:4096
	v_pk_mul_f32 v[64:65], v[64:65], v[100:101]
	s_nop 0
	v_cvt_pk_bf16_f32 v64, v64, v65
	ds_write_b16 v112, v64 offset:4096
	ds_write_b16_d16_hi v113, v64 offset:4096
	v_mov_b32_e32 v64, v82
	v_mov_b32_e32 v65, v66
	v_pk_add_f32 v[64:65], v[64:65], v[160:161]
	s_nop 0
	v_mul_f32_e32 v66, 0xbfb8aa3b, v64
	v_exp_f32_e32 v66, v66
	v_mul_f32_e32 v80, 0xbfb8aa3b, v65
	v_exp_f32_e32 v81, v80
	v_add_f32_e32 v66, 1.0, v66
	v_rcp_f32_e32 v80, v66
	v_add_f32_e32 v66, 1.0, v81
	v_rcp_f32_e32 v81, v66
	v_mov_b32_e32 v66, v83
	v_pk_add_f32 v[66:67], v[66:67], v[160:161]
	v_pk_mul_f32 v[64:65], v[64:65], v[80:81]
	v_mul_f32_e32 v82, 0xbfb8aa3b, v66
	v_mul_f32_e32 v83, 0xbfb8aa3b, v67
	v_exp_f32_e32 v82, v82
	v_exp_f32_e32 v83, v83
	v_cvt_pk_bf16_f32 v64, v64, v65
	ds_write_b16 v96, v64 offset:4096
	ds_write_b16_d16_hi v97, v64 offset:4096
	v_add_f32_e32 v80, 1.0, v82
	v_add_f32_e32 v81, 1.0, v83
	v_rcp_f32_e32 v80, v80
	v_rcp_f32_e32 v81, v81
	s_nop 0
	v_pk_mul_f32 v[64:65], v[66:67], v[80:81]
	s_nop 0
	v_cvt_pk_bf16_f32 v64, v64, v65
	ds_write_b16 v98, v64 offset:4096
	ds_write_b16_d16_hi v99, v64 offset:4096
	v_mov_b32_e32 v64, v84
	v_mov_b32_e32 v65, v68
	v_pk_add_f32 v[64:65], v[64:65], v[160:161]
	v_mov_b32_e32 v68, v85
	v_mul_f32_e32 v66, 0xbfb8aa3b, v64
	v_mul_f32_e32 v67, 0xbfb8aa3b, v65
	v_exp_f32_e32 v66, v66
	v_exp_f32_e32 v67, v67
	v_pk_add_f32 v[68:69], v[68:69], v[160:161]
	v_add_f32_e32 v66, 1.0, v66
	v_add_f32_e32 v67, 1.0, v67
	v_mul_f32_e32 v80, 0xbfb8aa3b, v68
	v_mul_f32_e32 v81, 0xbfb8aa3b, v69
	v_rcp_f32_e32 v66, v66
	v_rcp_f32_e32 v67, v67
	v_exp_f32_e32 v80, v80
	v_exp_f32_e32 v81, v81
	v_pk_mul_f32 v[64:65], v[64:65], v[66:67]
	v_add_f32_e32 v66, 1.0, v80
	v_add_f32_e32 v67, 1.0, v81
	v_rcp_f32_e32 v66, v66
	v_rcp_f32_e32 v67, v67
	v_cvt_pk_bf16_f32 v64, v64, v65
	ds_write_b16 v144, v64 offset:5120
	ds_write_b16_d16_hi v190, v64 offset:5120
	v_pk_mul_f32 v[64:65], v[68:69], v[66:67]
	s_nop 0
	v_cvt_pk_bf16_f32 v64, v64, v65
	ds_write_b16 v112, v64 offset:5120
	ds_write_b16_d16_hi v113, v64 offset:5120
	v_mov_b32_e32 v64, v86
	v_mov_b32_e32 v65, v70
	v_pk_add_f32 v[64:65], v[64:65], v[160:161]
	v_mov_b32_e32 v70, v87
	v_mul_f32_e32 v66, 0xbfb8aa3b, v64
	v_mul_f32_e32 v67, 0xbfb8aa3b, v65
	v_exp_f32_e32 v66, v66
	v_exp_f32_e32 v67, v67
	v_pk_add_f32 v[68:69], v[70:71], v[160:161]
	v_add_f32_e32 v66, 1.0, v66
	v_add_f32_e32 v67, 1.0, v67
	v_mul_f32_e32 v70, 0xbfb8aa3b, v68
	v_mul_f32_e32 v71, 0xbfb8aa3b, v69
	v_rcp_f32_e32 v66, v66
	v_rcp_f32_e32 v67, v67
	v_exp_f32_e32 v70, v70
	v_exp_f32_e32 v71, v71
	v_pk_mul_f32 v[64:65], v[64:65], v[66:67]
	v_add_f32_e32 v66, 1.0, v70
	v_add_f32_e32 v67, 1.0, v71
	v_rcp_f32_e32 v66, v66
	v_rcp_f32_e32 v67, v67
	v_cvt_pk_bf16_f32 v64, v64, v65
	ds_write_b16 v96, v64 offset:5120
	ds_write_b16_d16_hi v97, v64 offset:5120
	v_pk_mul_f32 v[64:65], v[68:69], v[66:67]
	s_nop 0
	v_cvt_pk_bf16_f32 v64, v64, v65
	ds_write_b16 v98, v64 offset:5120
	ds_write_b16_d16_hi v99, v64 offset:5120
	v_mov_b32_e32 v64, v88
	v_mov_b32_e32 v65, v72
	v_pk_add_f32 v[64:65], v[64:65], v[160:161]
	v_mov_b32_e32 v72, v89
	v_mul_f32_e32 v66, 0xbfb8aa3b, v64
	v_mul_f32_e32 v67, 0xbfb8aa3b, v65
	v_exp_f32_e32 v66, v66
	v_exp_f32_e32 v67, v67
	v_pk_add_f32 v[68:69], v[72:73], v[160:161]
	v_add_f32_e32 v66, 1.0, v66
	v_add_f32_e32 v67, 1.0, v67
	v_mul_f32_e32 v70, 0xbfb8aa3b, v68
	v_mul_f32_e32 v71, 0xbfb8aa3b, v69
	v_rcp_f32_e32 v66, v66
	v_rcp_f32_e32 v67, v67
	v_exp_f32_e32 v70, v70
	v_exp_f32_e32 v71, v71
	v_pk_mul_f32 v[64:65], v[64:65], v[66:67]
	v_add_f32_e32 v66, 1.0, v70
	v_add_f32_e32 v67, 1.0, v71
	v_rcp_f32_e32 v66, v66
	v_rcp_f32_e32 v67, v67
	v_cvt_pk_bf16_f32 v64, v64, v65
	ds_write_b16 v144, v64 offset:6144
	ds_write_b16_d16_hi v190, v64 offset:6144
	v_pk_mul_f32 v[64:65], v[68:69], v[66:67]
	s_nop 0
	v_cvt_pk_bf16_f32 v64, v64, v65
	ds_write_b16 v112, v64 offset:6144
	ds_write_b16_d16_hi v113, v64 offset:6144
	v_mov_b32_e32 v64, v90
	v_mov_b32_e32 v65, v74
	v_pk_add_f32 v[64:65], v[64:65], v[160:161]
	v_mov_b32_e32 v74, v91
	v_mul_f32_e32 v66, 0xbfb8aa3b, v64
	v_mul_f32_e32 v67, 0xbfb8aa3b, v65
	v_exp_f32_e32 v66, v66
	v_exp_f32_e32 v67, v67
	v_pk_add_f32 v[68:69], v[74:75], v[160:161]
	v_add_f32_e32 v66, 1.0, v66
	v_add_f32_e32 v67, 1.0, v67
	v_mul_f32_e32 v70, 0xbfb8aa3b, v68
	v_mul_f32_e32 v71, 0xbfb8aa3b, v69
	v_rcp_f32_e32 v66, v66
	v_rcp_f32_e32 v67, v67
	v_exp_f32_e32 v70, v70
	v_exp_f32_e32 v71, v71
	v_pk_mul_f32 v[64:65], v[64:65], v[66:67]
	v_add_f32_e32 v66, 1.0, v70
	v_add_f32_e32 v67, 1.0, v71
	v_rcp_f32_e32 v66, v66
	v_rcp_f32_e32 v67, v67
	v_cvt_pk_bf16_f32 v64, v64, v65
	ds_write_b16 v96, v64 offset:6144
	ds_write_b16_d16_hi v97, v64 offset:6144
	v_pk_mul_f32 v[64:65], v[68:69], v[66:67]
	s_nop 0
	v_cvt_pk_bf16_f32 v64, v64, v65
	ds_write_b16 v98, v64 offset:6144
	ds_write_b16_d16_hi v99, v64 offset:6144
	v_mov_b32_e32 v64, v92
	v_mov_b32_e32 v65, v76
	v_pk_add_f32 v[64:65], v[64:65], v[160:161]
	v_mov_b32_e32 v76, v93
	v_mul_f32_e32 v66, 0xbfb8aa3b, v64
	v_mul_f32_e32 v67, 0xbfb8aa3b, v65
	v_exp_f32_e32 v66, v66
	v_exp_f32_e32 v67, v67
	v_pk_add_f32 v[68:69], v[76:77], v[160:161]
	v_add_f32_e32 v66, 1.0, v66
	v_add_f32_e32 v67, 1.0, v67
	v_mul_f32_e32 v70, 0xbfb8aa3b, v68
	v_mul_f32_e32 v71, 0xbfb8aa3b, v69
	v_rcp_f32_e32 v66, v66
	v_rcp_f32_e32 v67, v67
	v_exp_f32_e32 v70, v70
	v_exp_f32_e32 v71, v71
	v_add_u32_e32 v76, 8, v158
	v_pk_mul_f32 v[64:65], v[64:65], v[66:67]
	v_add_f32_e32 v66, 1.0, v70
	v_add_f32_e32 v67, 1.0, v71
	v_rcp_f32_e32 v66, v66
	v_rcp_f32_e32 v67, v67
	v_cvt_pk_bf16_f32 v64, v64, v65
	ds_write_b16 v144, v64 offset:7168
	ds_write_b16_d16_hi v190, v64 offset:7168
	v_ashrrev_i32_e32 v77, 31, v76
	v_pk_mul_f32 v[64:65], v[68:69], v[66:67]
	s_nop 0
	v_cvt_pk_bf16_f32 v64, v64, v65
	ds_write_b16 v112, v64 offset:7168
	ds_write_b16_d16_hi v113, v64 offset:7168
	v_mov_b32_e32 v64, v94
	v_mov_b32_e32 v65, v78
	v_pk_add_f32 v[64:65], v[64:65], v[160:161]
	v_mov_b32_e32 v78, v95
	v_mul_f32_e32 v66, 0xbfb8aa3b, v64
	v_mul_f32_e32 v67, 0xbfb8aa3b, v65
	v_exp_f32_e32 v66, v66
	v_exp_f32_e32 v67, v67
	v_pk_add_f32 v[68:69], v[78:79], v[160:161]
	v_add_f32_e32 v66, 1.0, v66
	v_add_f32_e32 v67, 1.0, v67
	v_mul_f32_e32 v70, 0xbfb8aa3b, v68
	v_mul_f32_e32 v71, 0xbfb8aa3b, v69
	v_rcp_f32_e32 v66, v66
	v_rcp_f32_e32 v67, v67
	v_exp_f32_e32 v70, v70
	v_exp_f32_e32 v71, v71
	v_pk_mul_f32 v[64:65], v[64:65], v[66:67]
	v_add_f32_e32 v66, 1.0, v70
	v_add_f32_e32 v67, 1.0, v71
	v_rcp_f32_e32 v66, v66
	v_rcp_f32_e32 v67, v67
	v_cvt_pk_bf16_f32 v64, v64, v65
	ds_write_b16 v96, v64 offset:7168
	ds_write_b16_d16_hi v97, v64 offset:7168
	v_pk_mul_f32 v[64:65], v[68:69], v[66:67]
	s_nop 0
	v_cvt_pk_bf16_f32 v64, v64, v65
	ds_write_b16 v98, v64 offset:7168
	ds_write_b16_d16_hi v99, v64 offset:7168
	v_xor_b32_e32 v64, v158, v159
	v_lshlrev_b32_e32 v64, 4, v64
	v_and_b32_e32 v64, 0x70, v64
	v_add_u32_e32 v78, v169, v64
	v_lshlrev_b32_e32 v64, 4, v159
	v_and_b32_e32 v144, 0x70, v64
	v_lshl_add_u32 v64, v158, 7, v78
	v_ashrrev_i32_e32 v159, 31, v158
	v_lshl_add_u64 v[72:73], v[156:157], 0, v[144:145]
	ds_read_b128 v[64:67], v64
	v_lshlrev_b64 v[68:69], 9, v[158:159]
	v_lshl_add_u64 v[74:75], v[72:73], 0, v[68:69]
	v_lshl_add_u32 v68, v76, 7, v78
	ds_read_b128 v[68:71], v68
	s_waitcnt lgkmcnt(1)
	global_store_dwordx4 v[74:75], v[64:67], off
	s_nop 1
	v_lshlrev_b64 v[64:65], 9, v[76:77]
	v_lshl_add_u64 v[64:65], v[72:73], 0, v[64:65]
	s_waitcnt lgkmcnt(0)
	global_store_dwordx4 v[64:65], v[68:71], off
	v_add_u32_e32 v76, 24, v158
	v_ashrrev_i32_e32 v77, 31, v76
	v_add_u32_e32 v68, 16, v158
	v_lshl_add_u32 v64, v68, 7, v78
	v_ashrrev_i32_e32 v69, 31, v68
	ds_read_b128 v[64:67], v64
	v_lshlrev_b64 v[68:69], 9, v[68:69]
	v_lshl_add_u64 v[74:75], v[72:73], 0, v[68:69]
	v_lshl_add_u32 v68, v76, 7, v78
	ds_read_b128 v[68:71], v68
	s_waitcnt lgkmcnt(1)
	global_store_dwordx4 v[74:75], v[64:67], off
	s_nop 1
	v_lshlrev_b64 v[64:65], 9, v[76:77]
	v_lshl_add_u64 v[64:65], v[72:73], 0, v[64:65]
	s_waitcnt lgkmcnt(0)
	global_store_dwordx4 v[64:65], v[68:71], off
	v_add_u32_e32 v76, 40, v158
	v_ashrrev_i32_e32 v77, 31, v76
	v_add_u32_e32 v68, 32, v158
	v_lshl_add_u32 v64, v68, 7, v78
	v_ashrrev_i32_e32 v69, 31, v68
	ds_read_b128 v[64:67], v64
	v_lshlrev_b64 v[68:69], 9, v[68:69]
	v_lshl_add_u64 v[74:75], v[72:73], 0, v[68:69]
	v_lshl_add_u32 v68, v76, 7, v78
	ds_read_b128 v[68:71], v68
	s_waitcnt lgkmcnt(1)
	global_store_dwordx4 v[74:75], v[64:67], off
	s_nop 1
	v_lshlrev_b64 v[64:65], 9, v[76:77]
	v_lshl_add_u64 v[64:65], v[72:73], 0, v[64:65]
	s_waitcnt lgkmcnt(0)
	global_store_dwordx4 v[64:65], v[68:71], off
	v_add_u32_e32 v76, 56, v158
	v_ashrrev_i32_e32 v77, 31, v76
	v_add_u32_e32 v68, 48, v158
	v_lshl_add_u32 v64, v68, 7, v78
	v_ashrrev_i32_e32 v69, 31, v68
	ds_read_b128 v[64:67], v64
	v_lshlrev_b64 v[68:69], 9, v[68:69]
	v_lshl_add_u64 v[74:75], v[72:73], 0, v[68:69]
	v_lshl_add_u32 v68, v76, 7, v78
	ds_read_b128 v[68:71], v68
	s_waitcnt lgkmcnt(1)
	global_store_dwordx4 v[74:75], v[64:67], off
	s_nop 1
	v_lshlrev_b64 v[64:65], 9, v[76:77]
	v_lshl_add_u64 v[64:65], v[72:73], 0, v[64:65]
	s_waitcnt lgkmcnt(0)
	global_store_dwordx4 v[64:65], v[68:71], off
	v_mov_b32_e32 v65, v141
	s_nop 0
	v_and_b32_e32 v64, 31, v65
	v_or3_b32 v66, v170, v64, s6
	v_ashrrev_i32_e32 v67, 31, v66
	v_lshl_add_u64 v[68:69], v[66:67], 2, s[12:13]
	global_load_dword v66, v[68:69], off
	global_load_dword v67, v[68:69], off offset:128
	s_nop 0
	v_ashrrev_i32_e32 v64, 3, v65
	v_and_b32_e32 v68, -4, v64
	v_lshrrev_b32_e32 v72, 3, v65
	v_lshlrev_b32_e32 v69, 7, v68
	v_bfi_b32 v71, 3, v72, v64
	v_lshl_add_u32 v73, v71, 4, v69
	v_lshlrev_b32_e32 v69, 1, v65
	v_bfe_u32 v70, v65, 3, 2
	v_and_b32_e32 v74, 14, v69
	v_or_b32_e32 v69, 1, v68
	v_lshlrev_b32_e32 v69, 7, v69
	v_bitop3_b32 v71, v68, v70, 1 bitop3:0x36
	v_lshl_add_u32 v75, v71, 4, v69
	v_or_b32_e32 v69, 2, v68
	v_lshlrev_b32_e32 v69, 7, v69
	v_bitop3_b32 v68, v68, v70, 2 bitop3:0x36
	v_lshl_add_u32 v76, v68, 4, v69
	v_mov_b32_e32 v68, v48
	v_mov_b32_e32 v69, v32
	v_or_b32_e32 v77, 3, v64
	v_or_b32_e32 v75, v75, v74
	s_waitcnt vmcnt(0)
	v_pk_add_f32 v[68:69], v[68:69], v[66:67]
	s_nop 0
	v_mul_f32_e32 v32, 0xbfb8aa3b, v68
	v_exp_f32_e32 v32, v32
	v_mul_f32_e32 v48, 0xbfb8aa3b, v69
	v_exp_f32_e32 v48, v48
	v_add_f32_e32 v32, 1.0, v32
	v_rcp_f32_e32 v70, v32
	v_add_f32_e32 v32, 1.0, v48
	v_rcp_f32_e32 v71, v32
	v_lshlrev_b32_e32 v32, 7, v77
	v_bitop3_b32 v48, v72, v64, 3 bitop3:0x4e
	v_lshl_add_u32 v77, v48, 4, v32
	v_mov_b32_e32 v32, v49
	v_pk_add_f32 v[48:49], v[32:33], v[66:67]
	v_pk_mul_f32 v[68:69], v[68:69], v[70:71]
	v_mul_f32_e32 v32, 0xbfb8aa3b, v48
	v_exp_f32_e32 v33, v32
	v_mul_f32_e32 v32, 0xbfb8aa3b, v49
	v_cvt_pk_bf16_f32 v70, v68, v69
	v_exp_f32_e32 v69, v32
	v_add_f32_e32 v33, 1.0, v33
	v_rcp_f32_e32 v68, v33
	v_or_b32_e32 v71, v73, v74
	v_add_f32_e32 v33, 1.0, v69
	v_rcp_f32_e32 v69, v33
	v_add_u32_e32 v32, v169, v71
	v_xad_u32 v33, v71, 64, v169
	ds_write_b16 v32, v70
	v_pk_mul_f32 v[48:49], v[48:49], v[68:69]
	v_mov_b32_e32 v68, v50
	v_mov_b32_e32 v69, v34
	ds_write_b16_d16_hi v33, v70
	v_pk_add_f32 v[70:71], v[68:69], v[66:67]
	v_cvt_pk_bf16_f32 v49, v48, v49
	v_mul_f32_e32 v34, 0xbfb8aa3b, v70
	v_exp_f32_e32 v34, v34
	v_mul_f32_e32 v50, 0xbfb8aa3b, v71
	v_exp_f32_e32 v50, v50
	v_add_u32_e32 v48, v169, v75
	v_add_f32_e32 v34, 1.0, v34
	v_rcp_f32_e32 v72, v34
	v_add_f32_e32 v34, 1.0, v50
	v_rcp_f32_e32 v73, v34
	v_mov_b32_e32 v34, v51
	v_pk_add_f32 v[50:51], v[34:35], v[66:67]
	v_xad_u32 v68, v75, 64, v169
	v_mul_f32_e32 v34, 0xbfb8aa3b, v50
	v_pk_mul_f32 v[70:71], v[70:71], v[72:73]
	v_exp_f32_e32 v35, v34
	v_mul_f32_e32 v34, 0xbfb8aa3b, v51
	ds_write_b16 v48, v49
	ds_write_b16_d16_hi v68, v49
	v_cvt_pk_bf16_f32 v49, v70, v71
	v_exp_f32_e32 v71, v34
	v_add_f32_e32 v35, 1.0, v35
	v_rcp_f32_e32 v70, v35
	v_or_b32_e32 v69, v76, v74
	v_add_f32_e32 v35, 1.0, v71
	v_rcp_f32_e32 v71, v35
	v_add_u32_e32 v34, v169, v69
	v_xad_u32 v35, v69, 64, v169
	v_pk_mul_f32 v[50:51], v[50:51], v[70:71]
	v_mov_b32_e32 v70, v52
	v_mov_b32_e32 v71, v36
	v_cvt_pk_bf16_f32 v51, v50, v51
	v_or_b32_e32 v50, v77, v74
	v_pk_add_f32 v[70:71], v[70:71], v[66:67]
	ds_write_b16 v34, v49
	ds_write_b16_d16_hi v35, v49
	v_add_u32_e32 v49, v169, v50
	v_xad_u32 v50, v50, 64, v169
	v_mul_f32_e32 v36, 0xbfb8aa3b, v70
	ds_write_b16 v49, v51
	ds_write_b16_d16_hi v50, v51
	v_exp_f32_e32 v36, v36
	v_mul_f32_e32 v51, 0xbfb8aa3b, v71
	v_exp_f32_e32 v51, v51
	v_add_f32_e32 v36, 1.0, v36
	v_rcp_f32_e32 v72, v36
	v_add_f32_e32 v36, 1.0, v51
	v_rcp_f32_e32 v73, v36
	v_mov_b32_e32 v36, v53
	v_pk_add_f32 v[36:37], v[36:37], v[66:67]
	s_nop 0
	v_mul_f32_e32 v51, 0xbfb8aa3b, v36
	v_exp_f32_e32 v51, v51
	v_mul_f32_e32 v52, 0xbfb8aa3b, v37
	v_exp_f32_e32 v69, v52
	v_pk_mul_f32 v[52:53], v[70:71], v[72:73]
	v_add_f32_e32 v51, 1.0, v51
	v_rcp_f32_e32 v70, v51
	v_add_f32_e32 v51, 1.0, v69
	v_rcp_f32_e32 v71, v51
	v_cvt_pk_bf16_f32 v51, v52, v53
	ds_write_b16 v32, v51 offset:1024
	ds_write_b16_d16_hi v33, v51 offset:1024
	v_pk_mul_f32 v[36:37], v[36:37], v[70:71]
	s_nop 0
	v_cvt_pk_bf16_f32 v36, v36, v37
	ds_write_b16 v48, v36 offset:1024
	ds_write_b16_d16_hi v68, v36 offset:1024
	v_mov_b32_e32 v36, v54
	v_mov_b32_e32 v37, v38
	v_pk_add_f32 v[36:37], v[36:37], v[66:67]
	s_nop 0
	v_mul_f32_e32 v38, 0xbfb8aa3b, v36
	v_exp_f32_e32 v38, v38
	v_mul_f32_e32 v51, 0xbfb8aa3b, v37
	v_exp_f32_e32 v51, v51
	v_add_f32_e32 v38, 1.0, v38
	v_rcp_f32_e32 v52, v38
	v_add_f32_e32 v38, 1.0, v51
	v_rcp_f32_e32 v53, v38
	v_mov_b32_e32 v38, v55
	v_pk_add_f32 v[38:39], v[38:39], v[66:67]
	v_pk_mul_f32 v[36:37], v[36:37], v[52:53]
	v_mul_f32_e32 v51, 0xbfb8aa3b, v38
	v_exp_f32_e32 v51, v51
	v_mul_f32_e32 v54, 0xbfb8aa3b, v39
	v_exp_f32_e32 v54, v54
	v_cvt_pk_bf16_f32 v36, v36, v37
	v_add_f32_e32 v51, 1.0, v51
	v_rcp_f32_e32 v52, v51
	v_add_f32_e32 v51, 1.0, v54
	v_rcp_f32_e32 v53, v51
	ds_write_b16 v34, v36 offset:1024
	ds_write_b16_d16_hi v35, v36 offset:1024
	v_pk_mul_f32 v[36:37], v[38:39], v[52:53]
	s_nop 0
	v_cvt_pk_bf16_f32 v36, v36, v37
	ds_write_b16 v49, v36 offset:1024
	ds_write_b16_d16_hi v50, v36 offset:1024
	v_mov_b32_e32 v36, v56
	v_mov_b32_e32 v37, v40
	v_pk_add_f32 v[36:37], v[36:37], v[66:67]
	v_mov_b32_e32 v40, v57
	v_mul_f32_e32 v38, 0xbfb8aa3b, v36
	v_mul_f32_e32 v39, 0xbfb8aa3b, v37
	v_exp_f32_e32 v38, v38
	v_exp_f32_e32 v39, v39
	v_pk_add_f32 v[40:41], v[40:41], v[66:67]
	v_add_f32_e32 v38, 1.0, v38
	v_add_f32_e32 v39, 1.0, v39
	v_mul_f32_e32 v51, 0xbfb8aa3b, v40
	v_mul_f32_e32 v52, 0xbfb8aa3b, v41
	v_rcp_f32_e32 v38, v38
	v_rcp_f32_e32 v39, v39
	v_exp_f32_e32 v51, v51
	v_exp_f32_e32 v52, v52
	v_pk_mul_f32 v[36:37], v[36:37], v[38:39]
	v_add_f32_e32 v38, 1.0, v51
	v_add_f32_e32 v39, 1.0, v52
	v_rcp_f32_e32 v38, v38
	v_rcp_f32_e32 v39, v39
	v_cvt_pk_bf16_f32 v36, v36, v37
	ds_write_b16 v32, v36 offset:2048
	ds_write_b16_d16_hi v33, v36 offset:2048
	v_pk_mul_f32 v[36:37], v[40:41], v[38:39]
	s_nop 0
	v_cvt_pk_bf16_f32 v36, v36, v37
	ds_write_b16 v48, v36 offset:2048
	ds_write_b16_d16_hi v68, v36 offset:2048
	v_mov_b32_e32 v36, v58
	v_mov_b32_e32 v37, v42
	v_pk_add_f32 v[36:37], v[36:37], v[66:67]
	v_mov_b32_e32 v42, v59
	v_mul_f32_e32 v38, 0xbfb8aa3b, v36
	v_mul_f32_e32 v39, 0xbfb8aa3b, v37
	v_exp_f32_e32 v38, v38
	v_exp_f32_e32 v39, v39
	v_pk_add_f32 v[40:41], v[42:43], v[66:67]
	v_add_f32_e32 v38, 1.0, v38
	v_add_f32_e32 v39, 1.0, v39
	v_mul_f32_e32 v42, 0xbfb8aa3b, v40
	v_mul_f32_e32 v43, 0xbfb8aa3b, v41
	v_rcp_f32_e32 v38, v38
	v_rcp_f32_e32 v39, v39
	v_exp_f32_e32 v42, v42
	v_exp_f32_e32 v43, v43
	v_pk_mul_f32 v[36:37], v[36:37], v[38:39]
	v_add_f32_e32 v38, 1.0, v42
	v_add_f32_e32 v39, 1.0, v43
	v_rcp_f32_e32 v38, v38
	v_rcp_f32_e32 v39, v39
	v_cvt_pk_bf16_f32 v36, v36, v37
	ds_write_b16 v34, v36 offset:2048
	ds_write_b16_d16_hi v35, v36 offset:2048
	v_pk_mul_f32 v[36:37], v[40:41], v[38:39]
	s_nop 0
	v_cvt_pk_bf16_f32 v36, v36, v37
	ds_write_b16 v49, v36 offset:2048
	ds_write_b16_d16_hi v50, v36 offset:2048
	v_mov_b32_e32 v36, v60
	v_mov_b32_e32 v37, v44
	v_pk_add_f32 v[36:37], v[36:37], v[66:67]
	v_mov_b32_e32 v44, v61
	v_mul_f32_e32 v38, 0xbfb8aa3b, v36
	v_mul_f32_e32 v39, 0xbfb8aa3b, v37
	v_exp_f32_e32 v38, v38
	v_exp_f32_e32 v39, v39
	v_pk_add_f32 v[40:41], v[44:45], v[66:67]
	v_add_f32_e32 v38, 1.0, v38
	v_add_f32_e32 v39, 1.0, v39
	v_mul_f32_e32 v42, 0xbfb8aa3b, v40
	v_mul_f32_e32 v43, 0xbfb8aa3b, v41
	v_rcp_f32_e32 v38, v38
	v_rcp_f32_e32 v39, v39
	v_exp_f32_e32 v42, v42
	v_exp_f32_e32 v43, v43
	v_pk_mul_f32 v[36:37], v[36:37], v[38:39]
	v_add_f32_e32 v38, 1.0, v42
	v_add_f32_e32 v39, 1.0, v43
	v_rcp_f32_e32 v38, v38
	v_rcp_f32_e32 v39, v39
	v_cvt_pk_bf16_f32 v36, v36, v37
	ds_write_b16 v32, v36 offset:3072
	ds_write_b16_d16_hi v33, v36 offset:3072
	v_pk_mul_f32 v[36:37], v[40:41], v[38:39]
	s_nop 0
	v_cvt_pk_bf16_f32 v36, v36, v37
	ds_write_b16 v48, v36 offset:3072
	ds_write_b16_d16_hi v68, v36 offset:3072
	v_mov_b32_e32 v36, v62
	v_mov_b32_e32 v37, v46
	v_pk_add_f32 v[36:37], v[36:37], v[66:67]
	v_mov_b32_e32 v46, v63
	v_mul_f32_e32 v38, 0xbfb8aa3b, v36
	v_mul_f32_e32 v39, 0xbfb8aa3b, v37
	v_exp_f32_e32 v38, v38
	v_exp_f32_e32 v39, v39
	v_pk_add_f32 v[40:41], v[46:47], v[66:67]
	v_add_f32_e32 v38, 1.0, v38
	v_add_f32_e32 v39, 1.0, v39
	v_mul_f32_e32 v42, 0xbfb8aa3b, v40
	v_mul_f32_e32 v43, 0xbfb8aa3b, v41
	v_rcp_f32_e32 v38, v38
	v_rcp_f32_e32 v39, v39
	v_exp_f32_e32 v42, v42
	v_exp_f32_e32 v43, v43
	v_pk_mul_f32 v[36:37], v[36:37], v[38:39]
	v_add_f32_e32 v38, 1.0, v42
	v_add_f32_e32 v39, 1.0, v43
	v_rcp_f32_e32 v38, v38
	v_rcp_f32_e32 v39, v39
	v_cvt_pk_bf16_f32 v36, v36, v37
	ds_write_b16 v34, v36 offset:3072
	ds_write_b16_d16_hi v35, v36 offset:3072
	v_pk_mul_f32 v[36:37], v[40:41], v[38:39]
	s_nop 0
	v_cvt_pk_bf16_f32 v36, v36, v37
	ds_write_b16 v49, v36 offset:3072
	ds_write_b16_d16_hi v50, v36 offset:3072
	v_mov_b32_e32 v36, v16
	v_mov_b32_e32 v37, v0
	v_pk_add_f32 v[36:37], v[36:37], v[66:67]
	s_nop 0
	v_mul_f32_e32 v0, 0xbfb8aa3b, v36
	v_exp_f32_e32 v0, v0
	v_mul_f32_e32 v16, 0xbfb8aa3b, v37
	v_exp_f32_e32 v16, v16
	v_add_f32_e32 v0, 1.0, v0
	v_rcp_f32_e32 v38, v0
	v_add_f32_e32 v0, 1.0, v16
	v_rcp_f32_e32 v39, v0
	v_mov_b32_e32 v0, v17
	v_pk_add_f32 v[0:1], v[0:1], v[66:67]
	s_nop 0
	v_mul_f32_e32 v16, 0xbfb8aa3b, v0
	v_exp_f32_e32 v40, v16
	v_mul_f32_e32 v16, 0xbfb8aa3b, v1
	v_exp_f32_e32 v41, v16
	v_pk_mul_f32 v[16:17], v[36:37], v[38:39]
	v_add_f32_e32 v36, 1.0, v40
	v_rcp_f32_e32 v36, v36
	v_add_f32_e32 v37, 1.0, v41
	v_rcp_f32_e32 v37, v37
	v_cvt_pk_bf16_f32 v16, v16, v17
	ds_write_b16 v32, v16 offset:4096
	ds_write_b16_d16_hi v33, v16 offset:4096
	v_pk_mul_f32 v[0:1], v[0:1], v[36:37]
	s_nop 0
	v_cvt_pk_bf16_f32 v0, v0, v1
	ds_write_b16 v48, v0 offset:4096
	ds_write_b16_d16_hi v68, v0 offset:4096
	v_mov_b32_e32 v0, v18
	v_mov_b32_e32 v1, v2
	v_pk_add_f32 v[0:1], v[0:1], v[66:67]
	s_nop 0
	v_mul_f32_e32 v2, 0xbfb8aa3b, v0
	v_exp_f32_e32 v2, v2
	v_mul_f32_e32 v16, 0xbfb8aa3b, v1
	v_exp_f32_e32 v17, v16
	v_add_f32_e32 v2, 1.0, v2
	v_rcp_f32_e32 v16, v2
	v_add_f32_e32 v2, 1.0, v17
	v_rcp_f32_e32 v17, v2
	v_mov_b32_e32 v2, v19
	v_pk_add_f32 v[2:3], v[2:3], v[66:67]
	v_pk_mul_f32 v[0:1], v[0:1], v[16:17]
	v_mul_f32_e32 v18, 0xbfb8aa3b, v2
	v_mul_f32_e32 v19, 0xbfb8aa3b, v3
	v_exp_f32_e32 v18, v18
	v_exp_f32_e32 v19, v19
	v_cvt_pk_bf16_f32 v0, v0, v1
	ds_write_b16 v34, v0 offset:4096
	ds_write_b16_d16_hi v35, v0 offset:4096
	v_add_f32_e32 v16, 1.0, v18
	v_add_f32_e32 v17, 1.0, v19
	v_rcp_f32_e32 v16, v16
	v_rcp_f32_e32 v17, v17
	s_nop 0
	v_pk_mul_f32 v[0:1], v[2:3], v[16:17]
	s_nop 0
	v_cvt_pk_bf16_f32 v0, v0, v1
	ds_write_b16 v49, v0 offset:4096
	ds_write_b16_d16_hi v50, v0 offset:4096
	v_mov_b32_e32 v0, v20
	v_mov_b32_e32 v1, v4
	v_pk_add_f32 v[0:1], v[0:1], v[66:67]
	v_mov_b32_e32 v4, v21
	v_mul_f32_e32 v2, 0xbfb8aa3b, v0
	v_mul_f32_e32 v3, 0xbfb8aa3b, v1
	v_exp_f32_e32 v2, v2
	v_exp_f32_e32 v3, v3
	v_pk_add_f32 v[4:5], v[4:5], v[66:67]
	v_add_f32_e32 v2, 1.0, v2
	v_add_f32_e32 v3, 1.0, v3
	v_mul_f32_e32 v16, 0xbfb8aa3b, v4
	v_mul_f32_e32 v17, 0xbfb8aa3b, v5
	v_rcp_f32_e32 v2, v2
	v_rcp_f32_e32 v3, v3
	v_exp_f32_e32 v16, v16
	v_exp_f32_e32 v17, v17
	v_pk_mul_f32 v[0:1], v[0:1], v[2:3]
	v_add_f32_e32 v2, 1.0, v16
	v_add_f32_e32 v3, 1.0, v17
	v_rcp_f32_e32 v2, v2
	v_rcp_f32_e32 v3, v3
	v_cvt_pk_bf16_f32 v0, v0, v1
	ds_write_b16 v32, v0 offset:5120
	ds_write_b16_d16_hi v33, v0 offset:5120
	v_pk_mul_f32 v[0:1], v[4:5], v[2:3]
	s_nop 0
	v_cvt_pk_bf16_f32 v0, v0, v1
	ds_write_b16 v48, v0 offset:5120
	ds_write_b16_d16_hi v68, v0 offset:5120
	v_mov_b32_e32 v0, v22
	v_mov_b32_e32 v1, v6
	v_pk_add_f32 v[0:1], v[0:1], v[66:67]
	v_mov_b32_e32 v6, v23
	v_mul_f32_e32 v2, 0xbfb8aa3b, v0
	v_mul_f32_e32 v3, 0xbfb8aa3b, v1
	v_exp_f32_e32 v2, v2
	v_exp_f32_e32 v3, v3
	v_pk_add_f32 v[4:5], v[6:7], v[66:67]
	v_add_f32_e32 v2, 1.0, v2
	v_add_f32_e32 v3, 1.0, v3
	v_mul_f32_e32 v6, 0xbfb8aa3b, v4
	v_mul_f32_e32 v7, 0xbfb8aa3b, v5
	v_rcp_f32_e32 v2, v2
	v_rcp_f32_e32 v3, v3
	v_exp_f32_e32 v6, v6
	v_exp_f32_e32 v7, v7
	v_pk_mul_f32 v[0:1], v[0:1], v[2:3]
	v_add_f32_e32 v2, 1.0, v6
	v_add_f32_e32 v3, 1.0, v7
	v_rcp_f32_e32 v2, v2
	v_rcp_f32_e32 v3, v3
	v_cvt_pk_bf16_f32 v0, v0, v1
	ds_write_b16 v34, v0 offset:5120
	ds_write_b16_d16_hi v35, v0 offset:5120
	v_pk_mul_f32 v[0:1], v[4:5], v[2:3]
	s_nop 0
	v_cvt_pk_bf16_f32 v0, v0, v1
	ds_write_b16 v49, v0 offset:5120
	ds_write_b16_d16_hi v50, v0 offset:5120
	v_mov_b32_e32 v0, v24
	v_mov_b32_e32 v1, v8
	v_pk_add_f32 v[0:1], v[0:1], v[66:67]
	v_mov_b32_e32 v8, v25
	v_mul_f32_e32 v2, 0xbfb8aa3b, v0
	v_mul_f32_e32 v3, 0xbfb8aa3b, v1
	v_exp_f32_e32 v2, v2
	v_exp_f32_e32 v3, v3
	v_pk_add_f32 v[4:5], v[8:9], v[66:67]
	v_add_f32_e32 v2, 1.0, v2
	v_add_f32_e32 v3, 1.0, v3
	v_mul_f32_e32 v6, 0xbfb8aa3b, v4
	v_mul_f32_e32 v7, 0xbfb8aa3b, v5
	v_rcp_f32_e32 v2, v2
	v_rcp_f32_e32 v3, v3
	v_exp_f32_e32 v6, v6
	v_exp_f32_e32 v7, v7
	v_pk_mul_f32 v[0:1], v[0:1], v[2:3]
	v_add_f32_e32 v2, 1.0, v6
	v_add_f32_e32 v3, 1.0, v7
	v_rcp_f32_e32 v2, v2
	v_rcp_f32_e32 v3, v3
	v_cvt_pk_bf16_f32 v0, v0, v1
	ds_write_b16 v32, v0 offset:6144
	ds_write_b16_d16_hi v33, v0 offset:6144
	v_pk_mul_f32 v[0:1], v[4:5], v[2:3]
	s_nop 0
	v_cvt_pk_bf16_f32 v0, v0, v1
	ds_write_b16 v48, v0 offset:6144
	ds_write_b16_d16_hi v68, v0 offset:6144
	v_mov_b32_e32 v0, v26
	v_mov_b32_e32 v1, v10
	v_pk_add_f32 v[0:1], v[0:1], v[66:67]
	v_mov_b32_e32 v10, v27
	v_mul_f32_e32 v2, 0xbfb8aa3b, v0
	v_mul_f32_e32 v3, 0xbfb8aa3b, v1
	v_exp_f32_e32 v2, v2
	v_exp_f32_e32 v3, v3
	v_pk_add_f32 v[4:5], v[10:11], v[66:67]
	v_add_f32_e32 v2, 1.0, v2
	v_add_f32_e32 v3, 1.0, v3
	v_mul_f32_e32 v6, 0xbfb8aa3b, v4
	v_mul_f32_e32 v7, 0xbfb8aa3b, v5
	v_rcp_f32_e32 v2, v2
	v_rcp_f32_e32 v3, v3
	v_exp_f32_e32 v6, v6
	v_exp_f32_e32 v7, v7
	v_pk_mul_f32 v[0:1], v[0:1], v[2:3]
	v_add_f32_e32 v2, 1.0, v6
	v_add_f32_e32 v3, 1.0, v7
	v_rcp_f32_e32 v2, v2
	v_rcp_f32_e32 v3, v3
	v_cvt_pk_bf16_f32 v0, v0, v1
	ds_write_b16 v34, v0 offset:6144
	ds_write_b16_d16_hi v35, v0 offset:6144
	v_pk_mul_f32 v[0:1], v[4:5], v[2:3]
	s_nop 0
	v_cvt_pk_bf16_f32 v0, v0, v1
	ds_write_b16 v49, v0 offset:6144
	ds_write_b16_d16_hi v50, v0 offset:6144
	v_mov_b32_e32 v0, v28
	v_mov_b32_e32 v1, v12
	v_pk_add_f32 v[0:1], v[0:1], v[66:67]
	v_mov_b32_e32 v12, v29
	v_mul_f32_e32 v2, 0xbfb8aa3b, v0
	v_mul_f32_e32 v3, 0xbfb8aa3b, v1
	v_exp_f32_e32 v2, v2
	v_exp_f32_e32 v3, v3
	v_pk_add_f32 v[4:5], v[12:13], v[66:67]
	v_add_f32_e32 v2, 1.0, v2
	v_add_f32_e32 v3, 1.0, v3
	v_mul_f32_e32 v6, 0xbfb8aa3b, v4
	v_mul_f32_e32 v7, 0xbfb8aa3b, v5
	v_rcp_f32_e32 v2, v2
	v_rcp_f32_e32 v3, v3
	v_exp_f32_e32 v6, v6
	v_exp_f32_e32 v7, v7
	v_add_u32_e32 v12, 8, v64
	v_pk_mul_f32 v[0:1], v[0:1], v[2:3]
	v_add_f32_e32 v2, 1.0, v6
	v_add_f32_e32 v3, 1.0, v7
	v_rcp_f32_e32 v2, v2
	v_rcp_f32_e32 v3, v3
	v_cvt_pk_bf16_f32 v0, v0, v1
	ds_write_b16 v32, v0 offset:7168
	ds_write_b16_d16_hi v33, v0 offset:7168
	v_ashrrev_i32_e32 v13, 31, v12
	v_pk_mul_f32 v[0:1], v[4:5], v[2:3]
	s_nop 0
	v_cvt_pk_bf16_f32 v0, v0, v1
	ds_write_b16 v48, v0 offset:7168
	ds_write_b16_d16_hi v68, v0 offset:7168
	v_mov_b32_e32 v0, v30
	v_mov_b32_e32 v1, v14
	v_pk_add_f32 v[0:1], v[0:1], v[66:67]
	v_mov_b32_e32 v14, v31
	v_mul_f32_e32 v2, 0xbfb8aa3b, v0
	v_mul_f32_e32 v3, 0xbfb8aa3b, v1
	v_exp_f32_e32 v2, v2
	v_exp_f32_e32 v3, v3
	v_pk_add_f32 v[4:5], v[14:15], v[66:67]
	v_add_f32_e32 v2, 1.0, v2
	v_add_f32_e32 v3, 1.0, v3
	v_mul_f32_e32 v6, 0xbfb8aa3b, v4
	v_mul_f32_e32 v7, 0xbfb8aa3b, v5
	v_rcp_f32_e32 v2, v2
	v_rcp_f32_e32 v3, v3
	v_exp_f32_e32 v6, v6
	v_exp_f32_e32 v7, v7
	v_pk_mul_f32 v[0:1], v[0:1], v[2:3]
	v_add_f32_e32 v2, 1.0, v6
	v_add_f32_e32 v3, 1.0, v7
	v_rcp_f32_e32 v2, v2
	v_rcp_f32_e32 v3, v3
	v_cvt_pk_bf16_f32 v0, v0, v1
	ds_write_b16 v34, v0 offset:7168
	ds_write_b16_d16_hi v35, v0 offset:7168
	v_pk_mul_f32 v[0:1], v[4:5], v[2:3]
	s_nop 0
	v_cvt_pk_bf16_f32 v0, v0, v1
	ds_write_b16 v49, v0 offset:7168
	ds_write_b16_d16_hi v50, v0 offset:7168
	v_xor_b32_e32 v0, v64, v65
	v_lshlrev_b32_e32 v0, 4, v0
	v_and_b32_e32 v0, 0x70, v0
	v_add_u32_e32 v14, v169, v0
	v_lshlrev_b32_e32 v0, 4, v65
	v_and_b32_e32 v144, 0x70, v0
	v_lshl_add_u32 v0, v64, 7, v14
	v_ashrrev_i32_e32 v65, 31, v64
	v_lshl_add_u64 v[8:9], v[156:157], 0, v[144:145]
	ds_read_b128 v[0:3], v0
	v_lshlrev_b64 v[4:5], 9, v[64:65]
	v_lshl_add_u64 v[10:11], v[8:9], 0, v[4:5]
	v_lshl_add_u32 v4, v12, 7, v14
	ds_read_b128 v[4:7], v4
	s_waitcnt lgkmcnt(1)
	global_store_dwordx4 v[10:11], v[0:3], off offset:128
	s_nop 1
	v_lshlrev_b64 v[0:1], 9, v[12:13]
	v_lshl_add_u64 v[0:1], v[8:9], 0, v[0:1]
	s_waitcnt lgkmcnt(0)
	global_store_dwordx4 v[0:1], v[4:7], off offset:128
	v_add_u32_e32 v12, 24, v64
	v_ashrrev_i32_e32 v13, 31, v12
	v_add_u32_e32 v4, 16, v64
	v_lshl_add_u32 v0, v4, 7, v14
	v_ashrrev_i32_e32 v5, 31, v4
	ds_read_b128 v[0:3], v0
	v_lshlrev_b64 v[4:5], 9, v[4:5]
	v_lshl_add_u64 v[10:11], v[8:9], 0, v[4:5]
	v_lshl_add_u32 v4, v12, 7, v14
	ds_read_b128 v[4:7], v4
	s_waitcnt lgkmcnt(1)
	global_store_dwordx4 v[10:11], v[0:3], off offset:128
	s_nop 1
	v_lshlrev_b64 v[0:1], 9, v[12:13]
	v_lshl_add_u64 v[0:1], v[8:9], 0, v[0:1]
	s_waitcnt lgkmcnt(0)
	global_store_dwordx4 v[0:1], v[4:7], off offset:128
	v_add_u32_e32 v12, 40, v64
	v_ashrrev_i32_e32 v13, 31, v12
	v_add_u32_e32 v4, 32, v64
	v_lshl_add_u32 v0, v4, 7, v14
	v_ashrrev_i32_e32 v5, 31, v4
	ds_read_b128 v[0:3], v0
	v_lshlrev_b64 v[4:5], 9, v[4:5]
	v_lshl_add_u64 v[10:11], v[8:9], 0, v[4:5]
	v_lshl_add_u32 v4, v12, 7, v14
	ds_read_b128 v[4:7], v4
	s_waitcnt lgkmcnt(1)
	global_store_dwordx4 v[10:11], v[0:3], off offset:128
	s_nop 1
	v_lshlrev_b64 v[0:1], 9, v[12:13]
	v_lshl_add_u64 v[0:1], v[8:9], 0, v[0:1]
	s_waitcnt lgkmcnt(0)
	global_store_dwordx4 v[0:1], v[4:7], off offset:128
	v_add_u32_e32 v12, 56, v64
	v_ashrrev_i32_e32 v13, 31, v12
	v_add_u32_e32 v4, 48, v64
	v_lshl_add_u32 v0, v4, 7, v14
	v_ashrrev_i32_e32 v5, 31, v4
	ds_read_b128 v[0:3], v0
	v_lshlrev_b64 v[4:5], 9, v[4:5]
	v_lshl_add_u64 v[10:11], v[8:9], 0, v[4:5]
	v_lshl_add_u32 v4, v12, 7, v14
	ds_read_b128 v[4:7], v4
	s_waitcnt lgkmcnt(1)
	global_store_dwordx4 v[10:11], v[0:3], off offset:128
	s_nop 1
	v_lshlrev_b64 v[0:1], 9, v[12:13]
	v_lshl_add_u64 v[0:1], v[8:9], 0, v[0:1]
	s_waitcnt lgkmcnt(0)
	global_store_dwordx4 v[0:1], v[4:7], off offset:128
	s_cbranch_scc0 .LBB0_302

.LBB0_675:
	s_and_b32 s14, s13, 0x18000
	v_add_u32_e32 v138, s14, v161
	v_add_u32_e32 v139, 0x2000, v138
	v_readfirstlane_b32 s14, v138
	s_waitcnt vmcnt(8)
	v_lshl_add_u64 v[136:137], v[132:133], 0, s[8:9]
	s_mov_b32 m0, s14
	v_readfirstlane_b32 s14, v139
	v_add_u32_e32 v139, 0x4000, v138
	s_waitcnt lgkmcnt(0)
	s_barrier
	global_load_lds_dwordx4 v[136:137], off
	v_lshl_add_u64 v[136:137], v[134:135], 0, s[8:9]
	s_mov_b32 m0, s14
	v_readfirstlane_b32 s14, v139
	v_add_u32_e32 v138, 0x6000, v138
	global_load_lds_dwordx4 v[136:137], off
	v_lshl_add_u64 v[136:137], v[128:129], 0, s[8:9]
	s_mov_b32 m0, s14
	v_readfirstlane_b32 s14, v138
	global_load_lds_dwordx4 v[136:137], off
	v_lshl_add_u64 v[136:137], v[130:131], 0, s[8:9]
	s_mov_b32 m0, s14
	s_add_i32 s14, s13, 0xfffe8000
	global_load_lds_dwordx4 v[136:137], off
	s_and_b32 s14, s14, 0x18000
	s_add_i32 s14, s14, 16
	v_add_u32_e32 v144, s14, v162
	v_add_u32_e32 v156, s14, v164
	v_add_u32_e32 v140, v144, v163
	v_add_u32_e32 v157, v156, v163
	v_add_u32_e32 v190, s14, v166
	v_add_u32_e32 v144, v144, v167
	ds_read_b128 v[136:139], v140
	ds_read_b128 v[140:143], v140 offset:2048
	v_add_u32_e32 v192, v190, v163
	ds_read_b128 v[198:201], v157 offset:16384
	ds_read_b128 v[202:205], v192 offset:18432
	ds_read_b128 v[208:211], v192 offset:20480
	ds_read_b128 v[212:215], v192 offset:22528
	ds_read_b128 v[216:219], v144
	ds_read_b128 v[220:223], v144 offset:2048
	v_add_u32_e32 v144, v156, v167
	v_add_u32_e32 v156, v190, v167
	ds_read_b128 v[224:227], v144 offset:16384
	ds_read_b128 v[228:231], v156 offset:18432
	ds_read_b128 v[232:235], v156 offset:20480
	ds_read_b128 v[236:239], v156 offset:22528
	s_waitcnt lgkmcnt(9)
	v_mfma_f32_32x32x16_bf16 v[112:127], v[136:139], v[198:201], v[112:127]
	s_add_u32 s8, s8, 64
	s_addc_u32 s9, s9, 0
	s_add_i32 s13, s13, 0x8000
	s_cmpk_lg_i32 s8, 0x740
	s_waitcnt lgkmcnt(8)
	v_mfma_f32_32x32x16_bf16 v[96:111], v[136:139], v[202:205], v[96:111]
	s_waitcnt lgkmcnt(7)
	v_mfma_f32_32x32x16_bf16 v[48:63], v[136:139], v[208:211], v[48:63]
	s_waitcnt lgkmcnt(6)
	v_mfma_f32_32x32x16_bf16 v[32:47], v[136:139], v[212:215], v[32:47]
	v_mfma_f32_32x32x16_bf16 v[80:95], v[140:143], v[198:201], v[80:95]
	v_mfma_f32_32x32x16_bf16 v[64:79], v[140:143], v[202:205], v[64:79]
	v_mfma_f32_32x32x16_bf16 v[16:31], v[140:143], v[208:211], v[16:31]
	v_mfma_f32_32x32x16_bf16 v[0:15], v[140:143], v[212:215], v[0:15]
	s_waitcnt lgkmcnt(3)
	v_mfma_f32_32x32x16_bf16 v[112:127], v[216:219], v[224:227], v[112:127]
	s_waitcnt lgkmcnt(2)
	v_mfma_f32_32x32x16_bf16 v[96:111], v[216:219], v[228:231], v[96:111]
	s_waitcnt lgkmcnt(1)
	v_mfma_f32_32x32x16_bf16 v[48:63], v[216:219], v[232:235], v[48:63]
	s_waitcnt lgkmcnt(0)
	v_mfma_f32_32x32x16_bf16 v[32:47], v[216:219], v[236:239], v[32:47]
	v_mfma_f32_32x32x16_bf16 v[80:95], v[220:223], v[224:227], v[80:95]
	v_mfma_f32_32x32x16_bf16 v[64:79], v[220:223], v[228:231], v[64:79]
	v_mfma_f32_32x32x16_bf16 v[16:31], v[220:223], v[232:235], v[16:31]
	v_mfma_f32_32x32x16_bf16 v[0:15], v[220:223], v[236:239], v[0:15]
	s_cbranch_scc1 .LBB0_675
	s_waitcnt vmcnt(8)
	v_add_u32_e32 v132, v176, v163
	v_add_u32_e32 v136, v177, v163
	v_add_u32_e32 v144, v178, v163
	s_waitcnt lgkmcnt(0)
	s_barrier
	ds_read_b128 v[128:131], v132 offset:32768
	ds_read_b128 v[132:135], v132 offset:34816
	ds_read_b128 v[136:139], v136 offset:49152
	ds_read_b128 v[140:143], v144 offset:51200
	ds_read_b128 v[198:201], v144 offset:53248
	ds_read_b128 v[202:205], v144 offset:55296
	v_add_u32_e32 v144, v176, v167
	ds_read_b128 v[208:211], v144 offset:32768
	ds_read_b128 v[212:215], v144 offset:34816
	v_add_u32_e32 v144, v177, v167
	v_add_u32_e32 v156, v178, v167
	ds_read_b128 v[216:219], v144 offset:49152
	ds_read_b128 v[220:223], v156 offset:51200
	ds_read_b128 v[224:227], v156 offset:53248
	ds_read_b128 v[228:231], v156 offset:55296
	s_waitcnt lgkmcnt(0)
	v_mfma_f32_32x32x16_bf16 v[112:127], v[128:131], v[136:139], v[112:127]
	s_waitcnt vmcnt(4)
	v_add_u32_e32 v144, v173, v163
	s_waitcnt lgkmcnt(0)
	s_barrier
	v_add_u32_e32 v156, v174, v163
	v_mfma_f32_32x32x16_bf16 v[96:111], v[128:131], v[140:143], v[96:111]
	v_mfma_f32_32x32x16_bf16 v[48:63], v[128:131], v[198:201], v[48:63]
	v_mfma_f32_32x32x16_bf16 v[32:47], v[128:131], v[202:205], v[32:47]
	v_mfma_f32_32x32x16_bf16 v[80:95], v[132:135], v[136:139], v[80:95]
	v_add_u32_e32 v136, v175, v167
	v_mfma_f32_32x32x16_bf16 v[64:79], v[132:135], v[140:143], v[64:79]
	v_mfma_f32_32x32x16_bf16 v[16:31], v[132:135], v[198:201], v[16:31]
	v_mfma_f32_32x32x16_bf16 v[0:15], v[132:135], v[202:205], v[0:15]
	v_add_u32_e32 v132, v173, v167
	v_add_u32_e32 v133, v174, v167
	ds_read_b128 v[198:201], v132 offset:4096
	ds_read_b128 v[128:131], v132 offset:2048
	ds_read_b128 v[202:205], v132 offset:6144
	ds_read_b128 v[132:135], v133
	v_mfma_f32_32x32x16_bf16 v[112:127], v[208:211], v[216:219], v[112:127]
	v_mfma_f32_32x32x16_bf16 v[96:111], v[208:211], v[220:223], v[96:111]
	v_mfma_f32_32x32x16_bf16 v[48:63], v[208:211], v[224:227], v[48:63]
	v_mfma_f32_32x32x16_bf16 v[32:47], v[208:211], v[228:231], v[32:47]
	ds_read_b128 v[208:211], v136 offset:2048
	ds_read_b128 v[136:139], v136
	v_mfma_f32_32x32x16_bf16 v[80:95], v[212:215], v[216:219], v[80:95]
	ds_read_b128 v[140:143], v144 offset:4096
	ds_read_b128 v[216:219], v144 offset:2048
	v_mfma_f32_32x32x16_bf16 v[64:79], v[212:215], v[220:223], v[64:79]
	v_mfma_f32_32x32x16_bf16 v[16:31], v[212:215], v[224:227], v[16:31]
	ds_read_b128 v[220:223], v144 offset:6144
	ds_read_b128 v[224:227], v156
	v_add_u32_e32 v144, v175, v163
	ds_read_b128 v[232:235], v144 offset:2048
	ds_read_b128 v[236:239], v144
	v_mfma_f32_32x32x16_bf16 v[0:15], v[212:215], v[228:231], v[0:15]
	s_waitcnt lgkmcnt(0)
	v_mfma_f32_32x32x16_bf16 v[112:127], v[236:239], v[224:227], v[112:127]
	s_waitcnt vmcnt(0)
	v_add_u32_e32 v144, v168, v163
	s_waitcnt lgkmcnt(0)
	s_barrier
	v_add_u32_e32 v156, v169, v163
	v_mfma_f32_32x32x16_bf16 v[80:95], v[232:235], v[224:227], v[80:95]
	v_mfma_f32_32x32x16_bf16 v[96:111], v[236:239], v[216:219], v[96:111]
	v_mfma_f32_32x32x16_bf16 v[48:63], v[236:239], v[140:143], v[48:63]
	v_mfma_f32_32x32x16_bf16 v[32:47], v[236:239], v[220:223], v[32:47]
	v_mfma_f32_32x32x16_bf16 v[64:79], v[232:235], v[216:219], v[64:79]
	v_mfma_f32_32x32x16_bf16 v[16:31], v[232:235], v[140:143], v[16:31]
	v_add_u32_e32 v140, v170, v167
	v_mfma_f32_32x32x16_bf16 v[0:15], v[232:235], v[220:223], v[0:15]
	v_mfma_f32_32x32x16_bf16 v[112:127], v[136:139], v[132:135], v[112:127]
	v_mfma_f32_32x32x16_bf16 v[80:95], v[208:211], v[132:135], v[80:95]
	v_add_u32_e32 v132, v168, v167
	v_add_u32_e32 v133, v169, v167
	v_mfma_f32_32x32x16_bf16 v[96:111], v[136:139], v[128:131], v[96:111]
	v_mfma_f32_32x32x16_bf16 v[48:63], v[136:139], v[198:201], v[48:63]
	v_mfma_f32_32x32x16_bf16 v[32:47], v[136:139], v[202:205], v[32:47]
	ds_read_b128 v[136:139], v132 offset:4096
	ds_read_b128 v[212:215], v132 offset:2048
	v_mfma_f32_32x32x16_bf16 v[64:79], v[208:211], v[128:131], v[64:79]
	ds_read_b128 v[128:131], v132 offset:6144
	ds_read_b128 v[216:219], v133
	ds_read_b128 v[132:135], v140 offset:2048
	ds_read_b128 v[140:143], v140
	v_mfma_f32_32x32x16_bf16 v[16:31], v[208:211], v[198:201], v[16:31]
	ds_read_b128 v[198:201], v144 offset:4096
	ds_read_b128 v[220:223], v144 offset:2048
	ds_read_b128 v[224:227], v144 offset:6144
	ds_read_b128 v[228:231], v156
	v_add_u32_e32 v144, v170, v163
	ds_read_b128 v[232:235], v144 offset:2048
	ds_read_b128 v[236:239], v144
	v_mfma_f32_32x32x16_bf16 v[0:15], v[208:211], v[202:205], v[0:15]
	s_waitcnt lgkmcnt(0)
	v_mfma_f32_32x32x16_bf16 v[112:127], v[236:239], v[228:231], v[112:127]
	v_mov_b32_e32 v144, v158
	s_waitcnt lgkmcnt(0)
	s_barrier
	v_add_u32_e32 v156, s11, v171
	v_or_b32_e32 v202, s12, v165
	v_mfma_f32_32x32x16_bf16 v[96:111], v[236:239], v[220:223], v[96:111]
	v_and_b32_e32 v190, 31, v144
	v_lshlrev_b32_e32 v192, 5, v144
	v_and_b32_e32 v192, 0xfffffc00, v192
	v_lshlrev_b32_e32 v190, 2, v190
	v_add3_u32 v190, v172, v192, v190
	v_ashrrev_i32_e32 v157, 31, v156
	v_lshlrev_b64 v[204:205], 12, v[156:157]
	v_mfma_f32_32x32x16_bf16 v[80:95], v[232:235], v[228:231], v[80:95]
	v_ashrrev_i32_e32 v203, 31, v202
	v_lshl_add_u64 v[156:157], s[68:69], 0, v[204:205]
	v_lshlrev_b64 v[202:203], 2, v[202:203]
	v_lshl_add_u64 v[156:157], v[156:157], 0, v[202:203]
	s_add_i32 s10, s10, s50
	s_cmp_ge_i32 s10, s51
	v_mfma_f32_32x32x16_bf16 v[64:79], v[232:235], v[220:223], v[64:79]
	v_mfma_f32_32x32x16_bf16 v[112:127], v[140:143], v[216:219], v[112:127]
	v_mfma_f32_32x32x16_bf16 v[96:111], v[140:143], v[212:215], v[96:111]
	s_nop 11
	ds_write2_b32 v190, v112, v96 offset1:32
	ds_write2_b32 v190, v113, v97 offset0:64 offset1:96
	ds_write2_b32 v190, v114, v98 offset0:128 offset1:160
	ds_write2_b32 v190, v115, v99 offset0:192 offset1:224
	v_mfma_f32_32x32x16_bf16 v[80:95], v[132:135], v[216:219], v[80:95]
	v_add_u32_e32 v96, 0x800, v190
	ds_write2_b32 v96, v116, v100 offset1:32
	ds_write2_b32 v96, v117, v101 offset0:64 offset1:96
	ds_write2_b32 v96, v118, v102 offset0:128 offset1:160
	ds_write2_b32 v96, v119, v103 offset0:192 offset1:224
	v_add_u32_e32 v96, 0x1000, v190
	ds_write2_b32 v96, v120, v104 offset1:32
	ds_write2_b32 v96, v121, v105 offset0:64 offset1:96
	ds_write2_b32 v96, v122, v106 offset0:128 offset1:160
	ds_write2_b32 v96, v123, v107 offset0:192 offset1:224
	v_add_u32_e32 v96, 0x1800, v190
	v_mfma_f32_32x32x16_bf16 v[64:79], v[132:135], v[212:215], v[64:79]
	ds_write2_b32 v96, v124, v108 offset1:32
	ds_write2_b32 v96, v125, v109 offset0:64 offset1:96
	ds_write2_b32 v96, v126, v110 offset0:128 offset1:160
	ds_write2_b32 v96, v127, v111 offset0:192 offset1:224
	v_add_u32_e32 v96, 0x2000, v190
	s_nop 6
	ds_write2_b32 v96, v80, v64 offset1:32
	ds_write2_b32 v96, v81, v65 offset0:64 offset1:96
	ds_write2_b32 v96, v82, v66 offset0:128 offset1:160
	ds_write2_b32 v96, v83, v67 offset0:192 offset1:224
	v_add_u32_e32 v64, 0x2800, v190
	ds_write2_b32 v64, v84, v68 offset1:32
	ds_write2_b32 v64, v85, v69 offset0:64 offset1:96
	ds_write2_b32 v64, v86, v70 offset0:128 offset1:160
	ds_write2_b32 v64, v87, v71 offset0:192 offset1:224
	v_add_u32_e32 v64, 0x3000, v190
	ds_write2_b32 v64, v88, v72 offset1:32
	ds_write2_b32 v64, v89, v73 offset0:64 offset1:96
	ds_write2_b32 v64, v90, v74 offset0:128 offset1:160
	ds_write2_b32 v64, v91, v75 offset0:192 offset1:224
	v_add_u32_e32 v64, 0x3800, v190
	ds_write2_b32 v64, v92, v76 offset1:32
	ds_write2_b32 v64, v93, v77 offset0:64 offset1:96
	ds_write2_b32 v64, v94, v78 offset0:128 offset1:160
	ds_write2_b32 v64, v95, v79 offset0:192 offset1:224
	v_ashrrev_i32_e32 v70, 4, v144
	v_lshlrev_b32_e32 v64, 4, v144
	v_and_b32_e32 v144, 0xf0, v64
	v_ashrrev_i32_e32 v71, 31, v70
	v_add_u32_e32 v94, 4, v70
	v_lshl_add_u64 v[66:67], v[156:157], 0, v[144:145]
	v_lshlrev_b64 v[92:93], 12, v[70:71]
	v_ashrrev_i32_e32 v95, 31, v94
	v_lshl_add_u64 v[64:65], v[66:67], 0, v[92:93]
	v_lshlrev_b64 v[96:97], 12, v[94:95]
	global_load_dwordx4 v[72:75], v[64:65], off
	v_lshl_add_u64 v[64:65], v[66:67], 0, v[96:97]
	v_add_u32_e32 v98, 8, v70
	global_load_dwordx4 v[76:79], v[64:65], off
	v_ashrrev_i32_e32 v99, 31, v98
	v_add_u32_e32 v102, 12, v70
	v_lshlrev_b64 v[100:101], 12, v[98:99]
	v_ashrrev_i32_e32 v103, 31, v102
	v_lshl_add_u64 v[64:65], v[66:67], 0, v[100:101]
	v_lshlrev_b64 v[104:105], 12, v[102:103]
	global_load_dwordx4 v[80:83], v[64:65], off
	v_lshl_add_u64 v[64:65], v[66:67], 0, v[104:105]
	global_load_dwordx4 v[84:87], v[64:65], off
	v_lshl_add_u64 v[64:65], s[66:67], 0, v[204:205]
	v_add_u32_e32 v190, v172, v144
	v_lshl_add_u64 v[64:65], v[64:65], 0, v[202:203]
	v_lshl_add_u32 v71, v70, 8, v190
	v_lshl_add_u64 v[68:69], v[64:65], 0, v[144:145]
	ds_read_b128 v[88:91], v71
	v_lshl_add_u32 v71, v94, 8, v190
	v_lshl_add_u64 v[106:107], v[68:69], 0, v[92:93]
	ds_read_b128 v[92:95], v71
	v_lshl_add_u32 v71, v98, 8, v190
	v_lshl_add_u64 v[96:97], v[68:69], 0, v[96:97]
	v_lshl_add_u64 v[98:99], v[68:69], 0, v[100:101]
	v_add_u32_e32 v100, 28, v70
	v_ashrrev_i32_e32 v101, 31, v100
	v_mfma_f32_32x32x16_bf16 v[48:63], v[236:239], v[198:201], v[48:63]
	v_add_u32_e32 v108, 40, v70
	v_add_u32_e32 v110, 44, v70
	v_ashrrev_i32_e32 v109, 31, v108
	v_ashrrev_i32_e32 v111, 31, v110
	v_lshlrev_b64 v[116:117], 12, v[108:109]
	v_lshlrev_b64 v[118:119], 12, v[110:111]
	s_waitcnt vmcnt(0) lgkmcnt(0)
	v_pk_add_f32 v[72:73], v[72:73], v[88:89]
	v_pk_add_f32 v[74:75], v[74:75], v[90:91]
	ds_read_b128 v[88:91], v71
	v_lshl_add_u32 v71, v102, 8, v190
	v_pk_add_f32 v[76:77], v[76:77], v[92:93]
	v_pk_add_f32 v[78:79], v[78:79], v[94:95]
	ds_read_b128 v[92:95], v71
	v_lshlrev_b64 v[102:103], 12, v[100:101]
	v_mfma_f32_32x32x16_bf16 v[32:47], v[236:239], v[224:227], v[32:47]
	v_lshl_add_u32 v100, v100, 8, v190
	s_waitcnt lgkmcnt(1)
	v_add_f32_e64 v80, v80, v88
	v_add_f32_e64 v81, v81, v89
	v_lshl_add_u64 v[88:89], v[68:69], 0, v[104:105]
	v_pk_add_f32 v[82:83], v[82:83], v[90:91]
	s_waitcnt lgkmcnt(0)
	v_pk_add_f32 v[84:85], v[84:85], v[92:93]
	v_pk_add_f32 v[86:87], v[86:87], v[94:95]
	global_store_dwordx4 v[106:107], v[72:75], off
	global_store_dwordx4 v[96:97], v[76:79], off
	global_store_dwordx4 v[98:99], v[80:83], off
	global_store_dwordx4 v[88:89], v[84:87], off
	v_add_u32_e32 v88, 16, v70
	v_ashrrev_i32_e32 v89, 31, v88
	v_add_u32_e32 v92, 20, v70
	v_add_u32_e32 v96, 24, v70
	v_lshlrev_b64 v[90:91], 12, v[88:89]
	v_ashrrev_i32_e32 v93, 31, v92
	v_ashrrev_i32_e32 v97, 31, v96
	v_lshl_add_u64 v[72:73], v[66:67], 0, v[90:91]
	v_lshlrev_b64 v[94:95], 12, v[92:93]
	v_lshlrev_b64 v[98:99], 12, v[96:97]
	v_lshl_add_u64 v[76:77], v[66:67], 0, v[94:95]
	v_lshl_add_u64 v[80:81], v[66:67], 0, v[98:99]
	global_load_dwordx4 v[72:75], v[72:73], off
	v_lshl_add_u64 v[84:85], v[66:67], 0, v[102:103]
	global_load_dwordx4 v[76:79], v[76:77], off
	v_lshl_add_u32 v71, v88, 8, v190
	global_load_dwordx4 v[80:83], v[80:81], off
	v_lshl_add_u32 v92, v92, 8, v190
	global_load_dwordx4 v[84:87], v[84:85], off
	v_lshl_add_u32 v96, v96, 8, v190
	v_lshl_add_u64 v[120:121], v[68:69], 0, v[90:91]
	ds_read_b128 v[88:91], v71
	v_lshl_add_u64 v[122:123], v[68:69], 0, v[94:95]
	v_lshl_add_u64 v[124:125], v[68:69], 0, v[98:99]
	v_lshl_add_u64 v[126:127], v[68:69], 0, v[102:103]
	ds_read_b128 v[92:95], v92
	ds_read_b128 v[96:99], v96
	ds_read_b128 v[100:103], v100
	v_add_u32_e32 v104, 32, v70
	v_add_u32_e32 v106, 36, v70
	v_ashrrev_i32_e32 v105, 31, v104
	v_ashrrev_i32_e32 v107, 31, v106
	v_lshlrev_b64 v[112:113], 12, v[104:105]
	v_mfma_f32_32x32x16_bf16 v[48:63], v[140:143], v[136:139], v[48:63]
	v_lshlrev_b64 v[114:115], 12, v[106:107]
	v_lshl_add_u32 v71, v106, 8, v190
	s_waitcnt vmcnt(3) lgkmcnt(3)
	v_add_f32_e64 v72, v72, v88
	v_add_f32_e64 v73, v73, v89
	v_pk_add_f32 v[74:75], v[74:75], v[90:91]
	v_mfma_f32_32x32x16_bf16 v[32:47], v[140:143], v[128:131], v[32:47]
	v_lshl_add_u64 v[140:141], v[66:67], 0, v[112:113]
	s_waitcnt vmcnt(2) lgkmcnt(2)
	v_add_f32_e64 v76, v76, v92
	v_add_f32_e64 v77, v77, v93
	v_add_f32_e64 v78, v78, v94
	v_add_f32_e64 v79, v79, v95
	s_waitcnt vmcnt(1) lgkmcnt(1)
	v_pk_add_f32 v[80:81], v[80:81], v[96:97]
	v_pk_add_f32 v[82:83], v[82:83], v[98:99]
	s_waitcnt vmcnt(0) lgkmcnt(0)
	v_pk_add_f32 v[84:85], v[84:85], v[100:101]
	v_pk_add_f32 v[86:87], v[86:87], v[102:103]
	global_store_dwordx4 v[120:121], v[72:75], off
	global_store_dwordx4 v[122:123], v[76:79], off
	global_store_dwordx4 v[124:125], v[80:83], off
	global_store_dwordx4 v[126:127], v[84:87], off
	global_load_dwordx4 v[72:75], v[140:141], off
	v_lshl_add_u64 v[76:77], v[66:67], 0, v[114:115]
	v_lshl_add_u64 v[80:81], v[66:67], 0, v[116:117]
	v_lshl_add_u64 v[84:85], v[66:67], 0, v[118:119]
	global_load_dwordx4 v[76:79], v[76:77], off
	v_mfma_f32_32x32x16_bf16 v[16:31], v[232:235], v[198:201], v[16:31]
	global_load_dwordx4 v[80:83], v[80:81], off
	v_add_u32_e32 v120, 48, v70
	global_load_dwordx4 v[84:87], v[84:85], off
	v_add_u32_e32 v122, 52, v70
	v_add_u32_e32 v124, 56, v70
	v_add_u32_e32 v126, 60, v70
	v_lshl_add_u32 v70, v104, 8, v190
	v_lshl_add_u32 v96, v108, 8, v190
	v_lshl_add_u32 v100, v110, 8, v190
	ds_read_b128 v[88:91], v70
	ds_read_b128 v[92:95], v71
	ds_read_b128 v[96:99], v96
	ds_read_b128 v[100:103], v100
	v_ashrrev_i32_e32 v121, 31, v120
	v_ashrrev_i32_e32 v123, 31, v122
	v_ashrrev_i32_e32 v125, 31, v124
	v_ashrrev_i32_e32 v127, 31, v126
	v_lshlrev_b64 v[104:105], 12, v[120:121]
	v_lshl_add_u64 v[112:113], v[68:69], 0, v[112:113]
	v_mfma_f32_32x32x16_bf16 v[16:31], v[132:135], v[136:139], v[16:31]
	v_lshlrev_b64 v[106:107], 12, v[122:123]
	v_lshlrev_b64 v[108:109], 12, v[124:125]
	v_lshlrev_b64 v[110:111], 12, v[126:127]
	v_lshl_add_u64 v[114:115], v[68:69], 0, v[114:115]
	v_lshl_add_u64 v[116:117], v[68:69], 0, v[116:117]
	v_lshl_add_u64 v[118:119], v[68:69], 0, v[118:119]
	v_lshl_add_u64 v[136:137], v[66:67], 0, v[104:105]
	v_mfma_f32_32x32x16_bf16 v[0:15], v[232:235], v[224:227], v[0:15]
	s_waitcnt vmcnt(3) lgkmcnt(3)
	v_add_f32_e64 v70, v72, v88
	v_add_f32_e64 v71, v73, v89
	v_add_f32_e64 v72, v74, v90
	v_add_f32_e64 v73, v75, v91
	v_lshl_add_u32 v90, v124, 8, v190
	v_mfma_f32_32x32x16_bf16 v[0:15], v[132:135], v[128:131], v[0:15]
	s_waitcnt vmcnt(2) lgkmcnt(2)
	v_add_f32_e64 v74, v76, v92
	v_add_f32_e64 v75, v77, v93
	v_add_f32_e64 v76, v78, v94
	v_add_f32_e64 v77, v79, v95
	s_waitcnt vmcnt(1) lgkmcnt(1)
	v_pk_add_f32 v[78:79], v[80:81], v[96:97]
	v_pk_add_f32 v[80:81], v[82:83], v[98:99]
	s_waitcnt vmcnt(0) lgkmcnt(0)
	v_pk_add_f32 v[82:83], v[84:85], v[100:101]
	v_pk_add_f32 v[84:85], v[86:87], v[102:103]
	global_store_dwordx4 v[112:113], v[70:73], off
	global_store_dwordx4 v[114:115], v[74:77], off
	global_store_dwordx4 v[116:117], v[78:81], off
	global_store_dwordx4 v[118:119], v[82:85], off
	global_load_dwordx4 v[70:73], v[136:137], off
	v_lshl_add_u64 v[74:75], v[66:67], 0, v[106:107]
	v_lshl_add_u64 v[78:79], v[66:67], 0, v[108:109]
	v_lshl_add_u64 v[66:67], v[66:67], 0, v[110:111]
	global_load_dwordx4 v[74:77], v[74:75], off
	v_lshl_add_u32 v94, v126, 8, v190
	global_load_dwordx4 v[78:81], v[78:79], off
	v_lshl_add_u64 v[98:99], v[68:69], 0, v[104:105]
	global_load_dwordx4 v[82:85], v[66:67], off
	v_lshl_add_u32 v66, v120, 8, v190
	v_lshl_add_u32 v67, v122, 8, v190
	ds_read_b128 v[86:89], v66
	v_lshl_add_u64 v[100:101], v[68:69], 0, v[106:107]
	v_lshl_add_u64 v[102:103], v[68:69], 0, v[108:109]
	v_lshl_add_u64 v[104:105], v[68:69], 0, v[110:111]
	ds_read_b128 v[66:69], v67
	ds_read_b128 v[90:93], v90
	ds_read_b128 v[94:97], v94
	v_mov_b32_e32 v112, v158
	s_waitcnt vmcnt(3) lgkmcnt(3)
	v_pk_add_f32 v[70:71], v[70:71], v[86:87]
	v_pk_add_f32 v[72:73], v[72:73], v[88:89]
	s_waitcnt vmcnt(2) lgkmcnt(2)
	v_pk_add_f32 v[66:67], v[74:75], v[66:67]
	v_pk_add_f32 v[68:69], v[76:77], v[68:69]
	s_waitcnt vmcnt(1) lgkmcnt(1)
	v_pk_add_f32 v[74:75], v[78:79], v[90:91]
	v_pk_add_f32 v[76:77], v[80:81], v[92:93]
	s_waitcnt vmcnt(0) lgkmcnt(0)
	v_pk_add_f32 v[78:79], v[82:83], v[94:95]
	v_pk_add_f32 v[80:81], v[84:85], v[96:97]
	global_store_dwordx4 v[98:99], v[70:73], off
	global_store_dwordx4 v[100:101], v[66:69], off
	global_store_dwordx4 v[102:103], v[74:77], off
	global_store_dwordx4 v[104:105], v[78:81], off
	s_nop 0
	s_nop 0
	v_and_b32_e32 v66, 31, v112
	v_lshlrev_b32_e32 v67, 5, v112
	v_ashrrev_i32_e32 v68, 4, v112
	v_lshlrev_b32_e32 v69, 4, v112
	v_and_b32_e32 v67, 0xfffffc00, v67
	v_lshlrev_b32_e32 v66, 2, v66
	v_add_u32_e32 v70, 4, v68
	v_and_b32_e32 v144, 0xf0, v69
	v_ashrrev_i32_e32 v69, 31, v68
	v_add_u32_e32 v72, 8, v68
	v_add3_u32 v78, v172, v67, v66
	v_ashrrev_i32_e32 v71, 31, v70
	v_add_u32_e32 v74, 12, v68
	v_lshl_add_u64 v[66:67], v[156:157], 0, v[144:145]
	v_lshlrev_b64 v[76:77], 12, v[68:69]
	v_ashrrev_i32_e32 v73, 31, v72
	ds_write2_b32 v78, v48, v32 offset1:32
	ds_write2_b32 v78, v49, v33 offset0:64 offset1:96
	ds_write2_b32 v78, v50, v34 offset0:128 offset1:160
	ds_write2_b32 v78, v51, v35 offset0:192 offset1:224
	v_add_u32_e32 v69, 0x800, v78
	v_lshlrev_b64 v[34:35], 12, v[70:71]
	v_ashrrev_i32_e32 v75, 31, v74
	v_add_u32_e32 v79, 0x1000, v78
	v_add_u32_e32 v80, 0x1800, v78
	v_add_u32_e32 v81, 0x2000, v78
	v_add_u32_e32 v82, 0x2800, v78
	v_add_u32_e32 v83, 0x3000, v78
	v_add_u32_e32 v78, 0x3800, v78
	v_lshl_add_u64 v[32:33], v[66:67], 0, v[76:77]
	v_lshlrev_b64 v[48:49], 12, v[72:73]
	ds_write2_b32 v69, v52, v36 offset1:32
	ds_write2_b32 v69, v53, v37 offset0:64 offset1:96
	ds_write2_b32 v69, v54, v38 offset0:128 offset1:160
	ds_write2_b32 v69, v55, v39 offset0:192 offset1:224
	ds_write2_b32 v79, v56, v40 offset1:32
	ds_write2_b32 v79, v57, v41 offset0:64 offset1:96
	ds_write2_b32 v79, v58, v42 offset0:128 offset1:160
	ds_write2_b32 v79, v59, v43 offset0:192 offset1:224
	ds_write2_b32 v80, v60, v44 offset1:32
	ds_write2_b32 v80, v61, v45 offset0:64 offset1:96
	ds_write2_b32 v80, v62, v46 offset0:128 offset1:160
	ds_write2_b32 v80, v63, v47 offset0:192 offset1:224
	ds_write2_b32 v81, v16, v0 offset1:32
	ds_write2_b32 v81, v17, v1 offset0:64 offset1:96
	ds_write2_b32 v81, v18, v2 offset0:128 offset1:160
	ds_write2_b32 v81, v19, v3 offset0:192 offset1:224
	ds_write2_b32 v82, v20, v4 offset1:32
	ds_write2_b32 v82, v21, v5 offset0:64 offset1:96
	ds_write2_b32 v82, v22, v6 offset0:128 offset1:160
	ds_write2_b32 v82, v23, v7 offset0:192 offset1:224
	ds_write2_b32 v83, v24, v8 offset1:32
	ds_write2_b32 v83, v25, v9 offset0:64 offset1:96
	ds_write2_b32 v83, v26, v10 offset0:128 offset1:160
	ds_write2_b32 v83, v27, v11 offset0:192 offset1:224
	ds_write2_b32 v78, v28, v12 offset1:32
	ds_write2_b32 v78, v29, v13 offset0:64 offset1:96
	ds_write2_b32 v78, v30, v14 offset0:128 offset1:160
	ds_write2_b32 v78, v31, v15 offset0:192 offset1:224
	v_lshl_add_u64 v[0:1], v[66:67], 0, v[34:35]
	v_lshlrev_b64 v[50:51], 12, v[74:75]
	global_load_dwordx4 v[2:5], v[32:33], off offset:256
	global_load_dwordx4 v[6:9], v[0:1], off offset:256
	v_lshl_add_u64 v[0:1], v[66:67], 0, v[48:49]
	global_load_dwordx4 v[10:13], v[0:1], off offset:256
	v_lshl_add_u64 v[0:1], v[66:67], 0, v[50:51]
	global_load_dwordx4 v[14:17], v[0:1], off offset:256
	v_add_u32_e32 v60, v172, v144
	v_lshl_add_u32 v18, v68, 8, v60
	v_lshl_add_u32 v22, v70, 8, v60
	v_lshl_add_u32 v26, v72, 8, v60
	v_lshl_add_u32 v30, v74, 8, v60
	ds_read_b128 v[18:21], v18
	ds_read_b128 v[22:25], v22
	ds_read_b128 v[26:29], v26
	ds_read_b128 v[30:33], v30
	v_add_u32_e32 v36, 16, v68
	v_add_u32_e32 v38, 20, v68
	v_add_u32_e32 v40, 24, v68
	v_add_u32_e32 v42, 28, v68
	v_lshl_add_u64 v[0:1], v[64:65], 0, v[144:145]
	v_ashrrev_i32_e32 v37, 31, v36
	v_ashrrev_i32_e32 v39, 31, v38
	v_ashrrev_i32_e32 v41, 31, v40
	v_ashrrev_i32_e32 v43, 31, v42
	v_lshl_add_u64 v[44:45], v[0:1], 0, v[76:77]
	v_lshlrev_b64 v[46:47], 12, v[36:37]
	v_lshlrev_b64 v[52:53], 12, v[38:39]
	v_lshlrev_b64 v[54:55], 12, v[40:41]
	v_lshlrev_b64 v[56:57], 12, v[42:43]
	v_lshl_add_u64 v[34:35], v[0:1], 0, v[34:35]
	v_lshl_add_u64 v[48:49], v[0:1], 0, v[48:49]
	v_lshl_add_u64 v[50:51], v[0:1], 0, v[50:51]
	v_lshl_add_u64 v[58:59], v[66:67], 0, v[46:47]
	v_lshl_add_u64 v[46:47], v[0:1], 0, v[46:47]
	s_waitcnt vmcnt(3) lgkmcnt(3)
	v_pk_add_f32 v[2:3], v[2:3], v[18:19]
	v_pk_add_f32 v[4:5], v[4:5], v[20:21]
	s_waitcnt vmcnt(2) lgkmcnt(2)
	v_pk_add_f32 v[6:7], v[6:7], v[22:23]
	v_pk_add_f32 v[8:9], v[8:9], v[24:25]
	s_waitcnt vmcnt(1) lgkmcnt(1)
	v_pk_add_f32 v[10:11], v[10:11], v[26:27]
	v_pk_add_f32 v[12:13], v[12:13], v[28:29]
	s_waitcnt vmcnt(0) lgkmcnt(0)
	v_pk_add_f32 v[14:15], v[14:15], v[30:31]
	v_pk_add_f32 v[16:17], v[16:17], v[32:33]
	global_store_dwordx4 v[44:45], v[2:5], off offset:256
	global_store_dwordx4 v[34:35], v[6:9], off offset:256
	global_store_dwordx4 v[48:49], v[10:13], off offset:256
	global_store_dwordx4 v[50:51], v[14:17], off offset:256
	global_load_dwordx4 v[2:5], v[58:59], off offset:256
	v_lshl_add_u64 v[6:7], v[66:67], 0, v[52:53]
	v_lshl_add_u64 v[10:11], v[66:67], 0, v[54:55]
	v_lshl_add_u64 v[14:15], v[66:67], 0, v[56:57]
	global_load_dwordx4 v[6:9], v[6:7], off offset:256
	v_lshl_add_u32 v18, v36, 8, v60
	global_load_dwordx4 v[10:13], v[10:11], off offset:256
	v_lshl_add_u32 v22, v38, 8, v60
	global_load_dwordx4 v[14:17], v[14:15], off offset:256
	v_lshl_add_u32 v26, v40, 8, v60
	v_lshl_add_u32 v30, v42, 8, v60
	ds_read_b128 v[18:21], v18
	ds_read_b128 v[22:25], v22
	ds_read_b128 v[26:29], v26
	ds_read_b128 v[30:33], v30
	v_add_u32_e32 v34, 32, v68
	v_add_u32_e32 v44, 36, v68
	v_add_u32_e32 v48, 40, v68
	v_add_u32_e32 v50, 44, v68
	v_ashrrev_i32_e32 v35, 31, v34
	v_ashrrev_i32_e32 v45, 31, v44
	v_ashrrev_i32_e32 v49, 31, v48
	v_ashrrev_i32_e32 v51, 31, v50
	v_lshlrev_b64 v[36:37], 12, v[34:35]
	v_lshlrev_b64 v[38:39], 12, v[44:45]
	v_lshlrev_b64 v[40:41], 12, v[48:49]
	v_lshlrev_b64 v[42:43], 12, v[50:51]
	v_lshl_add_u64 v[52:53], v[0:1], 0, v[52:53]
	v_lshl_add_u64 v[54:55], v[0:1], 0, v[54:55]
	v_lshl_add_u64 v[56:57], v[0:1], 0, v[56:57]
	v_lshl_add_u64 v[58:59], v[66:67], 0, v[36:37]
	v_lshl_add_u64 v[36:37], v[0:1], 0, v[36:37]
	s_waitcnt vmcnt(3) lgkmcnt(3)
	v_pk_add_f32 v[2:3], v[2:3], v[18:19]
	v_pk_add_f32 v[4:5], v[4:5], v[20:21]
	v_lshl_add_u32 v18, v34, 8, v60
	s_waitcnt vmcnt(2) lgkmcnt(2)
	v_pk_add_f32 v[6:7], v[6:7], v[22:23]
	v_pk_add_f32 v[8:9], v[8:9], v[24:25]
	s_waitcnt vmcnt(1) lgkmcnt(1)
	v_pk_add_f32 v[10:11], v[10:11], v[26:27]
	v_pk_add_f32 v[12:13], v[12:13], v[28:29]
	s_waitcnt vmcnt(0) lgkmcnt(0)
	v_pk_add_f32 v[14:15], v[14:15], v[30:31]
	v_pk_add_f32 v[16:17], v[16:17], v[32:33]
	global_store_dwordx4 v[46:47], v[2:5], off offset:256
	global_store_dwordx4 v[52:53], v[6:9], off offset:256
	global_store_dwordx4 v[54:55], v[10:13], off offset:256
	global_store_dwordx4 v[56:57], v[14:17], off offset:256
	global_load_dwordx4 v[2:5], v[58:59], off offset:256
	v_lshl_add_u64 v[6:7], v[66:67], 0, v[38:39]
	v_lshl_add_u64 v[10:11], v[66:67], 0, v[40:41]
	v_lshl_add_u64 v[14:15], v[66:67], 0, v[42:43]
	global_load_dwordx4 v[6:9], v[6:7], off offset:256
	v_lshl_add_u32 v22, v44, 8, v60
	global_load_dwordx4 v[10:13], v[10:11], off offset:256
	v_lshl_add_u32 v26, v48, 8, v60
	global_load_dwordx4 v[14:17], v[14:15], off offset:256
	v_lshl_add_u32 v30, v50, 8, v60
	ds_read_b128 v[18:21], v18
	ds_read_b128 v[22:25], v22
	ds_read_b128 v[26:29], v26
	ds_read_b128 v[30:33], v30
	v_add_u32_e32 v46, 48, v68
	v_add_u32_e32 v52, 52, v68
	v_add_u32_e32 v54, 56, v68
	v_add_u32_e32 v56, 60, v68
	v_ashrrev_i32_e32 v47, 31, v46
	v_ashrrev_i32_e32 v53, 31, v52
	v_ashrrev_i32_e32 v55, 31, v54
	v_ashrrev_i32_e32 v57, 31, v56
	v_lshlrev_b64 v[34:35], 12, v[46:47]
	v_lshlrev_b64 v[44:45], 12, v[52:53]
	v_lshlrev_b64 v[48:49], 12, v[54:55]
	v_lshlrev_b64 v[50:51], 12, v[56:57]
	v_lshl_add_u64 v[38:39], v[0:1], 0, v[38:39]
	v_lshl_add_u64 v[40:41], v[0:1], 0, v[40:41]
	v_lshl_add_u64 v[42:43], v[0:1], 0, v[42:43]
	v_lshl_add_u64 v[58:59], v[66:67], 0, v[34:35]
	v_lshl_add_u64 v[34:35], v[0:1], 0, v[34:35]
	s_waitcnt vmcnt(3) lgkmcnt(3)
	v_pk_add_f32 v[2:3], v[2:3], v[18:19]
	v_pk_add_f32 v[4:5], v[4:5], v[20:21]
	v_lshl_add_u32 v18, v46, 8, v60
	s_waitcnt vmcnt(2) lgkmcnt(2)
	v_pk_add_f32 v[6:7], v[6:7], v[22:23]
	v_pk_add_f32 v[8:9], v[8:9], v[24:25]
	s_waitcnt vmcnt(1) lgkmcnt(1)
	v_pk_add_f32 v[10:11], v[10:11], v[26:27]
	v_pk_add_f32 v[12:13], v[12:13], v[28:29]
	s_waitcnt vmcnt(0) lgkmcnt(0)
	v_pk_add_f32 v[14:15], v[14:15], v[30:31]
	v_pk_add_f32 v[16:17], v[16:17], v[32:33]
	global_store_dwordx4 v[36:37], v[2:5], off offset:256
	global_store_dwordx4 v[38:39], v[6:9], off offset:256
	global_store_dwordx4 v[40:41], v[10:13], off offset:256
	global_store_dwordx4 v[42:43], v[14:17], off offset:256
	global_load_dwordx4 v[2:5], v[58:59], off offset:256
	v_lshl_add_u64 v[6:7], v[66:67], 0, v[44:45]
	v_lshl_add_u64 v[10:11], v[66:67], 0, v[48:49]
	v_lshl_add_u64 v[14:15], v[66:67], 0, v[50:51]
	global_load_dwordx4 v[6:9], v[6:7], off offset:256
	v_lshl_add_u32 v22, v52, 8, v60
	global_load_dwordx4 v[10:13], v[10:11], off offset:256
	v_lshl_add_u32 v26, v54, 8, v60
	global_load_dwordx4 v[14:17], v[14:15], off offset:256
	v_lshl_add_u32 v30, v56, 8, v60
	ds_read_b128 v[18:21], v18
	ds_read_b128 v[22:25], v22
	ds_read_b128 v[26:29], v26
	ds_read_b128 v[30:33], v30
	v_lshl_add_u64 v[36:37], v[0:1], 0, v[44:45]
	v_lshl_add_u64 v[38:39], v[0:1], 0, v[48:49]
	v_lshl_add_u64 v[40:41], v[0:1], 0, v[50:51]
	s_waitcnt vmcnt(3) lgkmcnt(3)
	v_pk_add_f32 v[0:1], v[2:3], v[18:19]
	v_pk_add_f32 v[2:3], v[4:5], v[20:21]
	s_waitcnt vmcnt(2) lgkmcnt(2)
	v_pk_add_f32 v[4:5], v[6:7], v[22:23]
	v_pk_add_f32 v[6:7], v[8:9], v[24:25]
	s_waitcnt vmcnt(1) lgkmcnt(1)
	v_pk_add_f32 v[8:9], v[10:11], v[26:27]
	v_pk_add_f32 v[10:11], v[12:13], v[28:29]
	s_waitcnt vmcnt(0) lgkmcnt(0)
	v_pk_add_f32 v[12:13], v[14:15], v[30:31]
	v_pk_add_f32 v[14:15], v[16:17], v[32:33]
	global_store_dwordx4 v[34:35], v[0:3], off offset:256
	global_store_dwordx4 v[36:37], v[4:7], off offset:256
	global_store_dwordx4 v[38:39], v[8:11], off offset:256
	global_store_dwordx4 v[40:41], v[12:15], off offset:256
	s_cbranch_scc0 .LBB0_674

.LBB0_789:
	s_and_b32 s13, s12, 0x18000
	v_add_u32_e32 v128, s13, v165
	v_add_u32_e32 v150, 0x2000, v128
	v_readfirstlane_b32 s13, v128
	s_waitcnt vmcnt(8)
	v_lshl_add_u64 v[148:149], v[144:145], 0, s[0:1]
	s_mov_b32 m0, s13
	v_readfirstlane_b32 s13, v150
	v_add_u32_e32 v150, 0x4000, v128
	s_waitcnt lgkmcnt(0)
	s_barrier
	global_load_lds_dwordx4 v[148:149], off
	v_lshl_add_u64 v[148:149], v[146:147], 0, s[0:1]
	s_mov_b32 m0, s13
	v_readfirstlane_b32 s13, v150
	v_add_u32_e32 v128, 0x6000, v128
	global_load_lds_dwordx4 v[148:149], off
	v_lshl_add_u64 v[148:149], v[140:141], 0, s[0:1]
	s_mov_b32 m0, s13
	v_readfirstlane_b32 s13, v128
	global_load_lds_dwordx4 v[148:149], off
	v_lshl_add_u64 v[148:149], v[142:143], 0, s[0:1]
	s_mov_b32 m0, s13
	s_add_i32 s13, s12, 0xfffe8000
	global_load_lds_dwordx4 v[148:149], off
	s_and_b32 s13, s13, 0x18000
	s_add_i32 s13, s13, 16
	v_add_u32_e32 v128, s13, v166
	v_add_u32_e32 v160, s13, v168
	v_add_u32_e32 v152, v128, v167
	v_add_u32_e32 v156, v160, v167
	v_add_u32_e32 v161, s13, v170
	v_add_u32_e32 v128, v128, v171
	ds_read_b128 v[148:151], v152
	ds_read_b128 v[152:155], v152 offset:2048
	v_add_u32_e32 v199, v161, v167
	ds_read_b128 v[156:159], v156 offset:16384
	ds_read_b128 v[200:203], v199 offset:18432
	ds_read_b128 v[208:211], v199 offset:20480
	ds_read_b128 v[212:215], v199 offset:22528
	ds_read_b128 v[216:219], v128
	ds_read_b128 v[220:223], v128 offset:2048
	v_add_u32_e32 v128, v160, v171
	v_add_u32_e32 v160, v161, v171
	ds_read_b128 v[224:227], v128 offset:16384
	ds_read_b128 v[228:231], v160 offset:18432
	ds_read_b128 v[232:235], v160 offset:20480
	ds_read_b128 v[236:239], v160 offset:22528
	s_waitcnt lgkmcnt(9)
	v_mfma_f32_32x32x16_bf16 v[112:127], v[148:151], v[156:159], v[112:127]
	s_add_u32 s0, s0, 64
	s_addc_u32 s1, s1, 0
	s_add_i32 s12, s12, 0x8000
	s_cmpk_eq_i32 s0, 0x740
	s_waitcnt lgkmcnt(8)
	v_mfma_f32_32x32x16_bf16 v[96:111], v[148:151], v[200:203], v[96:111]
	s_waitcnt lgkmcnt(7)
	v_mfma_f32_32x32x16_bf16 v[48:63], v[148:151], v[208:211], v[48:63]
	s_waitcnt lgkmcnt(6)
	v_mfma_f32_32x32x16_bf16 v[32:47], v[148:151], v[212:215], v[32:47]
	v_mfma_f32_32x32x16_bf16 v[80:95], v[152:155], v[156:159], v[80:95]
	v_mfma_f32_32x32x16_bf16 v[64:79], v[152:155], v[200:203], v[64:79]
	v_mfma_f32_32x32x16_bf16 v[16:31], v[152:155], v[208:211], v[16:31]
	v_mfma_f32_32x32x16_bf16 v[0:15], v[152:155], v[212:215], v[0:15]
	s_waitcnt lgkmcnt(3)
	v_mfma_f32_32x32x16_bf16 v[112:127], v[216:219], v[224:227], v[112:127]
	s_waitcnt lgkmcnt(2)
	v_mfma_f32_32x32x16_bf16 v[96:111], v[216:219], v[228:231], v[96:111]
	s_waitcnt lgkmcnt(1)
	v_mfma_f32_32x32x16_bf16 v[48:63], v[216:219], v[232:235], v[48:63]
	s_waitcnt lgkmcnt(0)
	v_mfma_f32_32x32x16_bf16 v[32:47], v[216:219], v[236:239], v[32:47]
	v_mfma_f32_32x32x16_bf16 v[80:95], v[220:223], v[224:227], v[80:95]
	v_mfma_f32_32x32x16_bf16 v[64:79], v[220:223], v[228:231], v[64:79]
	v_mfma_f32_32x32x16_bf16 v[16:31], v[220:223], v[232:235], v[16:31]
	v_mfma_f32_32x32x16_bf16 v[0:15], v[220:223], v[236:239], v[0:15]
	s_cbranch_scc0 .LBB0_789
	s_waitcnt vmcnt(8)
	v_add_u32_e32 v128, v180, v167
	s_waitcnt lgkmcnt(0)
	s_barrier
	ds_read_b128 v[140:143], v128 offset:32768
	ds_read_b128 v[144:147], v128 offset:34816
	v_add_u32_e32 v128, v181, v167
	v_add_u32_e32 v160, v182, v167
	ds_read_b128 v[148:151], v128 offset:49152
	ds_read_b128 v[152:155], v160 offset:51200
	ds_read_b128 v[156:159], v160 offset:53248
	ds_read_b128 v[200:203], v160 offset:55296
	v_add_u32_e32 v128, v180, v171
	ds_read_b128 v[208:211], v128 offset:32768
	ds_read_b128 v[212:215], v128 offset:34816
	v_add_u32_e32 v128, v181, v171
	v_add_u32_e32 v160, v182, v171
	ds_read_b128 v[216:219], v128 offset:49152
	ds_read_b128 v[220:223], v160 offset:51200
	ds_read_b128 v[224:227], v160 offset:53248
	ds_read_b128 v[228:231], v160 offset:55296
	s_waitcnt lgkmcnt(0)
	v_mfma_f32_32x32x16_bf16 v[112:127], v[140:143], v[148:151], v[112:127]
	s_waitcnt vmcnt(4)
	v_add_u32_e32 v128, v177, v171
	s_waitcnt lgkmcnt(0)
	s_barrier
	v_add_u32_e32 v160, v178, v167
	v_mfma_f32_32x32x16_bf16 v[96:111], v[140:143], v[152:155], v[96:111]
	v_mfma_f32_32x32x16_bf16 v[48:63], v[140:143], v[156:159], v[48:63]
	v_mfma_f32_32x32x16_bf16 v[32:47], v[140:143], v[200:203], v[32:47]
	v_mfma_f32_32x32x16_bf16 v[80:95], v[144:147], v[148:151], v[80:95]
	v_mfma_f32_32x32x16_bf16 v[64:79], v[144:147], v[152:155], v[64:79]
	v_add_u32_e32 v152, v178, v171
	v_mfma_f32_32x32x16_bf16 v[16:31], v[144:147], v[156:159], v[16:31]
	v_mfma_f32_32x32x16_bf16 v[0:15], v[144:147], v[200:203], v[0:15]
	ds_read_b128 v[140:143], v128 offset:4096
	ds_read_b128 v[144:147], v128 offset:2048
	ds_read_b128 v[148:151], v128 offset:6144
	ds_read_b128 v[152:155], v152
	v_add_u32_e32 v128, v179, v171
	ds_read_b128 v[156:159], v128 offset:2048
	ds_read_b128 v[200:203], v128
	v_add_u32_e32 v128, v177, v167
	v_mfma_f32_32x32x16_bf16 v[112:127], v[208:211], v[216:219], v[112:127]
	v_mfma_f32_32x32x16_bf16 v[96:111], v[208:211], v[220:223], v[96:111]
	v_mfma_f32_32x32x16_bf16 v[48:63], v[208:211], v[224:227], v[48:63]
	v_mfma_f32_32x32x16_bf16 v[32:47], v[208:211], v[228:231], v[32:47]
	v_mfma_f32_32x32x16_bf16 v[80:95], v[212:215], v[216:219], v[80:95]
	ds_read_b128 v[208:211], v128 offset:4096
	ds_read_b128 v[216:219], v128 offset:2048
	v_mfma_f32_32x32x16_bf16 v[64:79], v[212:215], v[220:223], v[64:79]
	v_mfma_f32_32x32x16_bf16 v[16:31], v[212:215], v[224:227], v[16:31]
	ds_read_b128 v[220:223], v128 offset:6144
	ds_read_b128 v[224:227], v160
	v_add_u32_e32 v128, v179, v167
	ds_read_b128 v[232:235], v128 offset:2048
	ds_read_b128 v[236:239], v128
	v_mfma_f32_32x32x16_bf16 v[0:15], v[212:215], v[228:231], v[0:15]
	s_waitcnt lgkmcnt(0)
	v_mfma_f32_32x32x16_bf16 v[112:127], v[236:239], v[224:227], v[112:127]
	s_waitcnt vmcnt(0)
	v_add_u32_e32 v128, v172, v171
	s_waitcnt lgkmcnt(0)
	s_barrier
	v_add_u32_e32 v160, v173, v171
	v_mfma_f32_32x32x16_bf16 v[96:111], v[236:239], v[216:219], v[96:111]
	v_mfma_f32_32x32x16_bf16 v[48:63], v[236:239], v[208:211], v[48:63]
	v_mfma_f32_32x32x16_bf16 v[32:47], v[236:239], v[220:223], v[32:47]
	v_mfma_f32_32x32x16_bf16 v[80:95], v[232:235], v[224:227], v[80:95]
	v_mfma_f32_32x32x16_bf16 v[64:79], v[232:235], v[216:219], v[64:79]
	v_mfma_f32_32x32x16_bf16 v[16:31], v[232:235], v[208:211], v[16:31]
	v_mfma_f32_32x32x16_bf16 v[0:15], v[232:235], v[220:223], v[0:15]
	v_mfma_f32_32x32x16_bf16 v[112:127], v[200:203], v[152:155], v[112:127]
	v_mfma_f32_32x32x16_bf16 v[96:111], v[200:203], v[144:147], v[96:111]
	v_mfma_f32_32x32x16_bf16 v[48:63], v[200:203], v[140:143], v[48:63]
	v_mfma_f32_32x32x16_bf16 v[32:47], v[200:203], v[148:151], v[32:47]
	v_mfma_f32_32x32x16_bf16 v[80:95], v[156:159], v[152:155], v[80:95]
	ds_read_b128 v[152:155], v128 offset:4096
	ds_read_b128 v[200:203], v128 offset:2048
	v_mfma_f32_32x32x16_bf16 v[64:79], v[156:159], v[144:147], v[64:79]
	ds_read_b128 v[144:147], v128 offset:6144
	ds_read_b128 v[208:211], v160
	v_add_u32_e32 v128, v174, v171
	ds_read_b128 v[212:215], v128 offset:2048
	ds_read_b128 v[216:219], v128
	v_add_u32_e32 v128, v172, v167
	v_add_u32_e32 v160, v173, v167
	v_mfma_f32_32x32x16_bf16 v[16:31], v[156:159], v[140:143], v[16:31]
	ds_read_b128 v[140:143], v128 offset:4096
	ds_read_b128 v[220:223], v128 offset:2048
	ds_read_b128 v[224:227], v128 offset:6144
	ds_read_b128 v[228:231], v160
	v_add_u32_e32 v128, v174, v167
	ds_read_b128 v[232:235], v128 offset:2048
	ds_read_b128 v[236:239], v128
	v_mfma_f32_32x32x16_bf16 v[0:15], v[156:159], v[148:151], v[0:15]
	s_waitcnt lgkmcnt(0)
	v_mfma_f32_32x32x16_bf16 v[112:127], v[236:239], v[228:231], v[112:127]
	s_waitcnt lgkmcnt(0)
	s_ashr_i32 s23, s10, 2
	s_and_b32 s0, s22, 0x300
	v_mov_b32_e32 v148, v162
	v_or_b32_e32 v199, s0, v169
	s_mov_b64 s[12:13], -1
	s_mov_b64 s[0:1], 0
	v_mfma_f32_32x32x16_bf16 v[96:111], v[236:239], v[220:223], v[96:111]
	s_cmp_lt_i32 s23, 2
	s_barrier
	v_mfma_f32_32x32x16_bf16 v[48:63], v[236:239], v[140:143], v[48:63]
	v_mfma_f32_32x32x16_bf16 v[32:47], v[236:239], v[224:227], v[32:47]
	v_mfma_f32_32x32x16_bf16 v[80:95], v[232:235], v[228:231], v[80:95]
	v_mfma_f32_32x32x16_bf16 v[64:79], v[232:235], v[220:223], v[64:79]
	v_mfma_f32_32x32x16_bf16 v[16:31], v[232:235], v[140:143], v[16:31]
	v_add_u32_e32 v140, s11, v175
	s_mov_b64 s[10:11], 0
	v_mfma_f32_32x32x16_bf16 v[0:15], v[232:235], v[224:227], v[0:15]
	v_mfma_f32_32x32x16_bf16 v[112:127], v[216:219], v[208:211], v[112:127]
	v_mfma_f32_32x32x16_bf16 v[96:111], v[216:219], v[200:203], v[96:111]
	v_mfma_f32_32x32x16_bf16 v[48:63], v[216:219], v[152:155], v[48:63]
	v_mfma_f32_32x32x16_bf16 v[32:47], v[216:219], v[144:147], v[32:47]
	v_mfma_f32_32x32x16_bf16 v[80:95], v[212:215], v[208:211], v[80:95]
	v_mfma_f32_32x32x16_bf16 v[64:79], v[212:215], v[200:203], v[64:79]
	v_mfma_f32_32x32x16_bf16 v[16:31], v[212:215], v[152:155], v[16:31]
	v_mfma_f32_32x32x16_bf16 v[0:15], v[212:215], v[144:147], v[0:15]
	s_cbranch_scc0 .LBB0_799
	s_and_b64 vcc, exec, s[12:13]
	s_cbranch_vccnz .LBB0_802

.LBB0_1048:
	s_and_b32 s11, s10, 0x18000
	s_add_i32 s12, s10, 0xfffe8000
	v_add_u32_e32 v128, s11, v151
	s_and_b32 s11, s12, 0x18000
	v_readfirstlane_b32 s12, v128
	v_add_u32_e32 v188, 0x2000, v128
	s_waitcnt vmcnt(8)
	v_lshl_add_u64 v[180:181], v[144:145], 0, s[6:7]
	v_add_u32_e32 v189, 0x4000, v128
	v_readfirstlane_b32 s13, v188
	s_mov_b32 m0, s12
	v_lshl_add_u64 v[182:183], v[146:147], 0, s[6:7]
	s_waitcnt lgkmcnt(0)
	s_barrier
	v_add_u32_e32 v128, 0x6000, v128
	v_readfirstlane_b32 s14, v189
	global_load_lds_dwordx4 v[180:181], off
	s_mov_b32 m0, s13
	v_lshl_add_u64 v[184:185], v[140:141], 0, s[6:7]
	v_readfirstlane_b32 s15, v128
	global_load_lds_dwordx4 v[182:183], off
	s_mov_b32 m0, s14
	v_lshl_add_u64 v[186:187], v[142:143], 0, s[6:7]
	global_load_lds_dwordx4 v[184:185], off
	s_mov_b32 m0, s15
	s_add_i32 s11, s11, 16
	global_load_lds_dwordx4 v[186:187], off
	v_add_u32_e32 v128, s11, v152
	v_add_u32_e32 v189, s11, v156
	v_add_u32_e32 v188, s11, v154
	v_add_u32_e32 v190, v128, v153
	v_add_u32_e32 v194, v189, v153
	v_add_u32_e32 v192, v188, v153
	ds_read_b128 v[180:183], v190
	ds_read_b128 v[184:187], v192 offset:16384
	ds_read_b128 v[198:201], v190 offset:2048
	ds_read_b128 v[202:205], v194 offset:18432
	ds_read_b128 v[208:211], v194 offset:20480
	ds_read_b128 v[212:215], v194 offset:22528
	s_waitcnt lgkmcnt(4)
	v_mfma_f32_32x32x16_bf16 v[112:127], v[180:183], v[184:187], v[112:127]
	v_add_u32_e32 v128, v128, v157
	s_add_u32 s6, s6, 64
	s_addc_u32 s7, s7, 0
	s_add_i32 s10, s10, 0x8000
	s_cmpk_lg_i32 s6, 0x740
	s_waitcnt lgkmcnt(2)
	v_mfma_f32_32x32x16_bf16 v[96:111], v[180:183], v[202:205], v[96:111]
	s_waitcnt lgkmcnt(1)
	v_mfma_f32_32x32x16_bf16 v[48:63], v[180:183], v[208:211], v[48:63]
	s_waitcnt lgkmcnt(0)
	v_mfma_f32_32x32x16_bf16 v[32:47], v[180:183], v[212:215], v[32:47]
	v_mfma_f32_32x32x16_bf16 v[80:95], v[198:201], v[184:187], v[80:95]
	v_add_u32_e32 v184, v188, v157
	v_add_u32_e32 v188, v189, v157
	v_mfma_f32_32x32x16_bf16 v[64:79], v[198:201], v[202:205], v[64:79]
	v_mfma_f32_32x32x16_bf16 v[16:31], v[198:201], v[208:211], v[16:31]
	v_mfma_f32_32x32x16_bf16 v[0:15], v[198:201], v[212:215], v[0:15]
	ds_read_b128 v[180:183], v128
	ds_read_b128 v[184:187], v184 offset:16384
	ds_read_b128 v[198:201], v128 offset:2048
	ds_read_b128 v[202:205], v188 offset:18432
	ds_read_b128 v[208:211], v188 offset:20480
	ds_read_b128 v[212:215], v188 offset:22528
	s_waitcnt lgkmcnt(4)
	v_mfma_f32_32x32x16_bf16 v[112:127], v[180:183], v[184:187], v[112:127]
	s_waitcnt lgkmcnt(2)
	v_mfma_f32_32x32x16_bf16 v[96:111], v[180:183], v[202:205], v[96:111]
	s_waitcnt lgkmcnt(1)
	v_mfma_f32_32x32x16_bf16 v[48:63], v[180:183], v[208:211], v[48:63]
	s_waitcnt lgkmcnt(0)
	v_mfma_f32_32x32x16_bf16 v[32:47], v[180:183], v[212:215], v[32:47]
	v_mfma_f32_32x32x16_bf16 v[80:95], v[198:201], v[184:187], v[80:95]
	v_mfma_f32_32x32x16_bf16 v[64:79], v[198:201], v[202:205], v[64:79]
	v_mfma_f32_32x32x16_bf16 v[16:31], v[198:201], v[208:211], v[16:31]
	v_mfma_f32_32x32x16_bf16 v[0:15], v[198:201], v[212:215], v[0:15]
	s_cbranch_scc1 .LBB0_1048
	s_waitcnt vmcnt(8)
	v_add_u32_e32 v128, v166, v153
	s_waitcnt lgkmcnt(0)
	s_barrier
	ds_read_b128 v[140:143], v128 offset:32768
	ds_read_b128 v[144:147], v128 offset:34816
	v_add_u32_e32 v128, v167, v153
	ds_read_b128 v[180:183], v128 offset:49152
	v_add_u32_e32 v128, v168, v153
	ds_read_b128 v[184:187], v128 offset:51200
	ds_read_b128 v[198:201], v128 offset:53248
	ds_read_b128 v[202:205], v128 offset:55296
	s_waitcnt lgkmcnt(0)
	v_mfma_f32_32x32x16_bf16 v[112:127], v[140:143], v[180:183], v[112:127]
	v_add_u32_e32 v128, v166, v157
	s_add_i32 s57, s57, s50
	s_cmp_ge_i32 s57, s51
	v_mfma_f32_32x32x16_bf16 v[96:111], v[140:143], v[184:187], v[96:111]
	v_mfma_f32_32x32x16_bf16 v[48:63], v[140:143], v[198:201], v[48:63]
	v_mfma_f32_32x32x16_bf16 v[32:47], v[140:143], v[202:205], v[32:47]
	v_mfma_f32_32x32x16_bf16 v[80:95], v[144:147], v[180:183], v[80:95]
	v_mfma_f32_32x32x16_bf16 v[64:79], v[144:147], v[184:187], v[64:79]
	v_mfma_f32_32x32x16_bf16 v[16:31], v[144:147], v[198:201], v[16:31]
	v_mfma_f32_32x32x16_bf16 v[0:15], v[144:147], v[202:205], v[0:15]
	ds_read_b128 v[140:143], v128 offset:32768
	ds_read_b128 v[144:147], v128 offset:34816
	v_add_u32_e32 v128, v167, v157
	ds_read_b128 v[180:183], v128 offset:49152
	v_add_u32_e32 v128, v168, v157
	ds_read_b128 v[184:187], v128 offset:51200
	ds_read_b128 v[198:201], v128 offset:53248
	ds_read_b128 v[202:205], v128 offset:55296
	s_waitcnt vmcnt(4)
	v_add_u32_e32 v128, v163, v157
	s_waitcnt lgkmcnt(0)
	v_mfma_f32_32x32x16_bf16 v[112:127], v[140:143], v[180:183], v[112:127]
	s_waitcnt lgkmcnt(0)
	s_barrier
	v_mfma_f32_32x32x16_bf16 v[96:111], v[140:143], v[184:187], v[96:111]
	v_mfma_f32_32x32x16_bf16 v[48:63], v[140:143], v[198:201], v[48:63]
	v_mfma_f32_32x32x16_bf16 v[32:47], v[140:143], v[202:205], v[32:47]
	v_mfma_f32_32x32x16_bf16 v[80:95], v[144:147], v[180:183], v[80:95]
	v_mfma_f32_32x32x16_bf16 v[64:79], v[144:147], v[184:187], v[64:79]
	v_mfma_f32_32x32x16_bf16 v[16:31], v[144:147], v[198:201], v[16:31]
	v_mfma_f32_32x32x16_bf16 v[0:15], v[144:147], v[202:205], v[0:15]
	ds_read_b128 v[140:143], v128 offset:6144
	ds_read_b128 v[144:147], v128 offset:4096
	ds_read_b128 v[180:183], v128 offset:2048
	v_add_u32_e32 v128, v164, v157
	ds_read_b128 v[184:187], v128
	v_add_u32_e32 v128, v165, v157
	ds_read_b128 v[198:201], v128 offset:2048
	ds_read_b128 v[202:205], v128
	v_add_u32_e32 v128, v163, v153
	ds_read_b128 v[208:211], v128 offset:6144
	ds_read_b128 v[212:215], v128 offset:4096
	ds_read_b128 v[216:219], v128 offset:2048
	v_add_u32_e32 v128, v164, v153
	ds_read_b128 v[220:223], v128
	v_add_u32_e32 v128, v165, v153
	ds_read_b128 v[224:227], v128 offset:2048
	ds_read_b128 v[228:231], v128
	s_waitcnt lgkmcnt(0)
	v_mfma_f32_32x32x16_bf16 v[96:111], v[228:231], v[216:219], v[96:111]
	s_waitcnt vmcnt(0)
	v_add_u32_e32 v128, v158, v157
	s_waitcnt lgkmcnt(0)
	s_barrier
	v_mfma_f32_32x32x16_bf16 v[48:63], v[228:231], v[212:215], v[48:63]
	v_mfma_f32_32x32x16_bf16 v[32:47], v[228:231], v[208:211], v[32:47]
	v_mfma_f32_32x32x16_bf16 v[64:79], v[224:227], v[216:219], v[64:79]
	v_mfma_f32_32x32x16_bf16 v[16:31], v[224:227], v[212:215], v[16:31]
	v_mfma_f32_32x32x16_bf16 v[0:15], v[224:227], v[208:211], v[0:15]
	v_mfma_f32_32x32x16_bf16 v[112:127], v[228:231], v[220:223], v[112:127]
	v_mfma_f32_32x32x16_bf16 v[80:95], v[224:227], v[220:223], v[80:95]
	v_mfma_f32_32x32x16_bf16 v[96:111], v[202:205], v[180:183], v[96:111]
	v_mfma_f32_32x32x16_bf16 v[48:63], v[202:205], v[144:147], v[48:63]
	v_mfma_f32_32x32x16_bf16 v[32:47], v[202:205], v[140:143], v[32:47]
	v_mfma_f32_32x32x16_bf16 v[64:79], v[198:201], v[180:183], v[64:79]
	v_mfma_f32_32x32x16_bf16 v[16:31], v[198:201], v[144:147], v[16:31]
	v_mfma_f32_32x32x16_bf16 v[0:15], v[198:201], v[140:143], v[0:15]
	ds_read_b128 v[140:143], v128 offset:6144
	ds_read_b128 v[144:147], v128 offset:4096
	ds_read_b128 v[180:183], v128 offset:2048
	v_add_u32_e32 v128, v159, v157
	v_mfma_f32_32x32x16_bf16 v[112:127], v[202:205], v[184:187], v[112:127]
	v_mfma_f32_32x32x16_bf16 v[80:95], v[198:201], v[184:187], v[80:95]
	ds_read_b128 v[184:187], v128
	v_add_u32_e32 v128, v160, v157
	ds_read_b128 v[198:201], v128 offset:2048
	ds_read_b128 v[202:205], v128
	v_add_u32_e32 v128, v158, v153
	ds_read_b128 v[208:211], v128 offset:6144
	ds_read_b128 v[212:215], v128 offset:4096
	ds_read_b128 v[216:219], v128 offset:2048
	v_add_u32_e32 v128, v159, v153
	ds_read_b128 v[220:223], v128
	v_add_u32_e32 v128, v160, v153
	ds_read_b128 v[224:227], v128 offset:2048
	ds_read_b128 v[228:231], v128
	s_waitcnt lgkmcnt(0)
	v_mfma_f32_32x32x16_bf16 v[112:127], v[228:231], v[220:223], v[112:127]
	v_mov_b32_e32 v128, v148
	s_waitcnt lgkmcnt(0)
	s_barrier
	s_nop 0
	v_mfma_f32_32x32x16_bf16 v[96:111], v[228:231], v[216:219], v[96:111]
	v_mfma_f32_32x32x16_bf16 v[32:47], v[228:231], v[208:211], v[32:47]
	v_mfma_f32_32x32x16_bf16 v[0:15], v[224:227], v[208:211], v[0:15]
	v_mfma_f32_32x32x16_bf16 v[80:95], v[224:227], v[220:223], v[80:95]
	v_mfma_f32_32x32x16_bf16 v[64:79], v[224:227], v[216:219], v[64:79]
	v_mfma_f32_32x32x16_bf16 v[112:127], v[202:205], v[184:187], v[112:127]
	v_mfma_f32_32x32x16_bf16 v[96:111], v[202:205], v[180:183], v[96:111]
	v_mfma_f32_32x32x16_bf16 v[32:47], v[202:205], v[140:143], v[32:47]
	v_mfma_f32_32x32x16_bf16 v[0:15], v[198:201], v[140:143], v[0:15]
	v_add_u32_e32 v140, s8, v161
	v_ashrrev_i32_e32 v141, 31, v140
	v_or_b32_e32 v142, s9, v155
	v_lshlrev_b64 v[140:141], 12, v[140:141]
	v_lshl_add_u64 v[140:141], s[66:67], 0, v[140:141]
	v_ashrrev_i32_e32 v143, 31, v142
	v_lshl_add_u64 v[140:141], v[142:143], 2, v[140:141]
	v_mfma_f32_32x32x16_bf16 v[80:95], v[198:201], v[184:187], v[80:95]
	v_and_b32_e32 v142, 31, v128
	v_lshlrev_b32_e32 v143, 5, v128
	v_and_b32_e32 v143, 0xfffffc00, v143
	v_lshlrev_b32_e32 v142, 2, v142
	v_add3_u32 v142, v162, v143, v142
	ds_write2_b32 v142, v112, v96 offset1:32
	ds_write2_b32 v142, v113, v97 offset0:64 offset1:96
	ds_write2_b32 v142, v114, v98 offset0:128 offset1:160
	ds_write2_b32 v142, v115, v99 offset0:192 offset1:224
	v_add_u32_e32 v96, 0x800, v142
	v_mfma_f32_32x32x16_bf16 v[64:79], v[198:201], v[180:183], v[64:79]
	ds_write2_b32 v96, v116, v100 offset1:32
	ds_write2_b32 v96, v117, v101 offset0:64 offset1:96
	ds_write2_b32 v96, v118, v102 offset0:128 offset1:160
	ds_write2_b32 v96, v119, v103 offset0:192 offset1:224
	v_add_u32_e32 v96, 0x1000, v142
	ds_write2_b32 v96, v120, v104 offset1:32
	ds_write2_b32 v96, v121, v105 offset0:64 offset1:96
	ds_write2_b32 v96, v122, v106 offset0:128 offset1:160
	ds_write2_b32 v96, v123, v107 offset0:192 offset1:224
	v_add_u32_e32 v96, 0x1800, v142
	ds_write2_b32 v96, v124, v108 offset1:32
	ds_write2_b32 v96, v125, v109 offset0:64 offset1:96
	ds_write2_b32 v96, v126, v110 offset0:128 offset1:160
	ds_write2_b32 v96, v127, v111 offset0:192 offset1:224
	v_add_u32_e32 v96, 0x2000, v142
	ds_write2_b32 v96, v80, v64 offset1:32
	ds_write2_b32 v96, v81, v65 offset0:64 offset1:96
	ds_write2_b32 v96, v82, v66 offset0:128 offset1:160
	ds_write2_b32 v96, v83, v67 offset0:192 offset1:224
	v_add_u32_e32 v64, 0x2800, v142
	ds_write2_b32 v64, v84, v68 offset1:32
	ds_write2_b32 v64, v85, v69 offset0:64 offset1:96
	ds_write2_b32 v64, v86, v70 offset0:128 offset1:160
	ds_write2_b32 v64, v87, v71 offset0:192 offset1:224
	v_add_u32_e32 v64, 0x3000, v142
	ds_write2_b32 v64, v88, v72 offset1:32
	ds_write2_b32 v64, v89, v73 offset0:64 offset1:96
	ds_write2_b32 v64, v90, v74 offset0:128 offset1:160
	ds_write2_b32 v64, v91, v75 offset0:192 offset1:224
	v_add_u32_e32 v64, 0x3800, v142
	ds_write2_b32 v64, v92, v76 offset1:32
	ds_write2_b32 v64, v93, v77 offset0:64 offset1:96
	ds_write2_b32 v64, v94, v78 offset0:128 offset1:160
	ds_write2_b32 v64, v95, v79 offset0:192 offset1:224
	v_ashrrev_i32_e32 v64, 4, v128
	v_lshlrev_b32_e32 v65, 4, v128
	v_and_b32_e32 v128, 0xf0, v65
	v_ashrrev_i32_e32 v65, 31, v64
	v_add_u32_e32 v80, 4, v64
	v_lshl_add_u64 v[66:67], v[140:141], 0, v[128:129]
	v_lshlrev_b64 v[70:71], 12, v[64:65]
	v_ashrrev_i32_e32 v81, 31, v80
	v_add_u32_e32 v84, 8, v64
	v_lshl_add_u64 v[78:79], v[66:67], 0, v[70:71]
	v_lshlrev_b64 v[70:71], 12, v[80:81]
	v_ashrrev_i32_e32 v85, 31, v84
	v_add_u32_e32 v88, 12, v64
	v_lshl_add_u64 v[82:83], v[66:67], 0, v[70:71]
	v_lshlrev_b64 v[70:71], 12, v[84:85]
	v_ashrrev_i32_e32 v89, 31, v88
	v_lshl_add_u64 v[86:87], v[66:67], 0, v[70:71]
	v_lshlrev_b64 v[70:71], 12, v[88:89]
	v_lshl_add_u64 v[90:91], v[66:67], 0, v[70:71]
	global_load_dwordx4 v[70:73], v[78:79], off
	v_add_u32_e32 v68, v162, v128
	v_lshl_add_u32 v65, v64, 8, v68
	ds_read_b128 v[74:77], v65
	v_lshl_add_u32 v65, v80, 8, v68
	v_add_u32_e32 v80, 20, v64
	v_ashrrev_i32_e32 v81, 31, v80
	v_mfma_f32_32x32x16_bf16 v[48:63], v[228:231], v[212:215], v[48:63]
	s_waitcnt vmcnt(0) lgkmcnt(0)
	v_add_f32_e64 v70, v70, v74
	v_add_f32_e64 v71, v71, v75
	v_add_f32_e64 v72, v72, v76
	v_add_f32_e64 v73, v73, v77
	global_store_dwordx4 v[78:79], v[70:73], off
	global_load_dwordx4 v[70:73], v[82:83], off
	ds_read_b128 v[74:77], v65
	v_lshl_add_u32 v65, v84, 8, v68
	v_add_u32_e32 v84, 24, v64
	v_ashrrev_i32_e32 v85, 31, v84
	v_mfma_f32_32x32x16_bf16 v[16:31], v[224:227], v[212:215], v[16:31]
	s_waitcnt vmcnt(0) lgkmcnt(0)
	v_add_f32_e64 v70, v70, v74
	v_add_f32_e64 v71, v71, v75
	v_add_f32_e64 v72, v72, v76
	v_add_f32_e64 v73, v73, v77
	global_store_dwordx4 v[82:83], v[70:73], off
	global_load_dwordx4 v[70:73], v[86:87], off
	ds_read_b128 v[74:77], v65
	v_lshl_add_u32 v65, v88, 8, v68
	v_add_u32_e32 v88, 28, v64
	v_ashrrev_i32_e32 v89, 31, v88
	v_mfma_f32_32x32x16_bf16 v[48:63], v[202:205], v[144:147], v[48:63]
	s_waitcnt vmcnt(0) lgkmcnt(0)
	v_add_f32_e64 v70, v70, v74
	v_add_f32_e64 v71, v71, v75
	v_add_f32_e64 v72, v72, v76
	v_add_f32_e64 v73, v73, v77
	global_store_dwordx4 v[86:87], v[70:73], off
	global_load_dwordx4 v[70:73], v[90:91], off
	ds_read_b128 v[74:77], v65
	v_mfma_f32_32x32x16_bf16 v[16:31], v[198:201], v[144:147], v[16:31]
	s_waitcnt vmcnt(0) lgkmcnt(0)
	v_add_f32_e64 v70, v70, v74
	v_add_f32_e64 v71, v71, v75
	v_add_f32_e64 v72, v72, v76
	v_add_f32_e64 v73, v73, v77
	global_store_dwordx4 v[90:91], v[70:73], off
	s_nop 1
	v_add_u32_e32 v70, 16, v64
	v_ashrrev_i32_e32 v71, 31, v70
	v_lshlrev_b64 v[72:73], 12, v[70:71]
	v_lshl_add_u64 v[78:79], v[66:67], 0, v[72:73]
	v_lshlrev_b64 v[72:73], 12, v[80:81]
	v_lshl_add_u64 v[82:83], v[66:67], 0, v[72:73]
	v_lshlrev_b64 v[72:73], 12, v[84:85]
	v_lshl_add_u64 v[86:87], v[66:67], 0, v[72:73]
	v_lshlrev_b64 v[72:73], 12, v[88:89]
	v_lshl_add_u64 v[90:91], v[66:67], 0, v[72:73]
	v_lshl_add_u32 v65, v70, 8, v68
	global_load_dwordx4 v[70:73], v[78:79], off
	ds_read_b128 v[74:77], v65
	v_lshl_add_u32 v65, v80, 8, v68
	v_add_u32_e32 v80, 36, v64
	v_ashrrev_i32_e32 v81, 31, v80
	s_waitcnt vmcnt(0) lgkmcnt(0)
	v_pk_add_f32 v[70:71], v[70:71], v[74:75]
	v_pk_add_f32 v[72:73], v[72:73], v[76:77]
	global_store_dwordx4 v[78:79], v[70:73], off
	global_load_dwordx4 v[70:73], v[82:83], off
	ds_read_b128 v[74:77], v65
	v_lshl_add_u32 v65, v84, 8, v68
	v_add_u32_e32 v84, 40, v64
	v_ashrrev_i32_e32 v85, 31, v84
	s_waitcnt vmcnt(0) lgkmcnt(0)
	v_pk_add_f32 v[70:71], v[70:71], v[74:75]
	v_pk_add_f32 v[72:73], v[72:73], v[76:77]
	global_store_dwordx4 v[82:83], v[70:73], off
	global_load_dwordx4 v[70:73], v[86:87], off
	ds_read_b128 v[74:77], v65
	v_lshl_add_u32 v65, v88, 8, v68
	v_add_u32_e32 v88, 44, v64
	v_ashrrev_i32_e32 v89, 31, v88
	s_waitcnt vmcnt(0) lgkmcnt(0)
	v_pk_add_f32 v[70:71], v[70:71], v[74:75]
	v_pk_add_f32 v[72:73], v[72:73], v[76:77]
	global_store_dwordx4 v[86:87], v[70:73], off
	global_load_dwordx4 v[70:73], v[90:91], off
	ds_read_b128 v[74:77], v65
	s_waitcnt vmcnt(0) lgkmcnt(0)
	v_pk_add_f32 v[70:71], v[70:71], v[74:75]
	v_pk_add_f32 v[72:73], v[72:73], v[76:77]
	global_store_dwordx4 v[90:91], v[70:73], off
	s_nop 1
	v_add_u32_e32 v70, 32, v64
	v_ashrrev_i32_e32 v71, 31, v70
	v_lshlrev_b64 v[72:73], 12, v[70:71]
	v_lshl_add_u64 v[78:79], v[66:67], 0, v[72:73]
	v_lshlrev_b64 v[72:73], 12, v[80:81]
	v_lshl_add_u64 v[82:83], v[66:67], 0, v[72:73]
	v_lshlrev_b64 v[72:73], 12, v[84:85]
	v_lshl_add_u64 v[86:87], v[66:67], 0, v[72:73]
	v_lshlrev_b64 v[72:73], 12, v[88:89]
	v_lshl_add_u64 v[90:91], v[66:67], 0, v[72:73]
	v_lshl_add_u32 v65, v70, 8, v68
	global_load_dwordx4 v[70:73], v[78:79], off
	ds_read_b128 v[74:77], v65
	v_lshl_add_u32 v65, v80, 8, v68
	v_add_u32_e32 v80, 52, v64
	v_ashrrev_i32_e32 v81, 31, v80
	s_waitcnt vmcnt(0) lgkmcnt(0)
	v_pk_add_f32 v[70:71], v[70:71], v[74:75]
	v_pk_add_f32 v[72:73], v[72:73], v[76:77]
	global_store_dwordx4 v[78:79], v[70:73], off
	global_load_dwordx4 v[70:73], v[82:83], off
	ds_read_b128 v[74:77], v65
	v_lshl_add_u32 v65, v84, 8, v68
	v_add_u32_e32 v84, 56, v64
	v_ashrrev_i32_e32 v85, 31, v84
	s_waitcnt vmcnt(0) lgkmcnt(0)
	v_pk_add_f32 v[70:71], v[70:71], v[74:75]
	v_pk_add_f32 v[72:73], v[72:73], v[76:77]
	global_store_dwordx4 v[82:83], v[70:73], off
	global_load_dwordx4 v[70:73], v[86:87], off
	ds_read_b128 v[74:77], v65
	v_lshl_add_u32 v65, v88, 8, v68
	v_add_u32_e32 v88, 60, v64
	v_ashrrev_i32_e32 v89, 31, v88
	s_waitcnt vmcnt(0) lgkmcnt(0)
	v_pk_add_f32 v[70:71], v[70:71], v[74:75]
	v_pk_add_f32 v[72:73], v[72:73], v[76:77]
	global_store_dwordx4 v[86:87], v[70:73], off
	global_load_dwordx4 v[70:73], v[90:91], off
	ds_read_b128 v[74:77], v65
	s_waitcnt vmcnt(0) lgkmcnt(0)
	v_pk_add_f32 v[70:71], v[70:71], v[74:75]
	v_pk_add_f32 v[72:73], v[72:73], v[76:77]
	global_store_dwordx4 v[90:91], v[70:73], off
	s_nop 1
	v_add_u32_e32 v70, 48, v64
	v_ashrrev_i32_e32 v71, 31, v70
	v_lshlrev_b64 v[72:73], 12, v[70:71]
	v_lshl_add_u64 v[78:79], v[66:67], 0, v[72:73]
	v_lshlrev_b64 v[72:73], 12, v[80:81]
	v_lshl_add_u64 v[82:83], v[66:67], 0, v[72:73]
	v_lshlrev_b64 v[72:73], 12, v[84:85]
	v_lshlrev_b64 v[64:65], 12, v[88:89]
	v_lshl_add_u64 v[86:87], v[66:67], 0, v[72:73]
	v_lshl_add_u64 v[64:65], v[66:67], 0, v[64:65]
	v_lshl_add_u32 v66, v70, 8, v68
	global_load_dwordx4 v[70:73], v[78:79], off
	ds_read_b128 v[74:77], v66
	v_lshl_add_u32 v66, v80, 8, v68
	s_waitcnt vmcnt(0) lgkmcnt(0)
	v_pk_add_f32 v[70:71], v[70:71], v[74:75]
	v_pk_add_f32 v[72:73], v[72:73], v[76:77]
	global_store_dwordx4 v[78:79], v[70:73], off
	global_load_dwordx4 v[70:73], v[82:83], off
	ds_read_b128 v[74:77], v66
	v_lshl_add_u32 v66, v84, 8, v68
	s_waitcnt vmcnt(0) lgkmcnt(0)
	v_pk_add_f32 v[70:71], v[70:71], v[74:75]
	v_pk_add_f32 v[72:73], v[72:73], v[76:77]
	global_store_dwordx4 v[82:83], v[70:73], off
	global_load_dwordx4 v[70:73], v[86:87], off
	ds_read_b128 v[74:77], v66
	s_waitcnt vmcnt(0) lgkmcnt(0)
	v_pk_add_f32 v[70:71], v[70:71], v[74:75]
	v_pk_add_f32 v[72:73], v[72:73], v[76:77]
	global_store_dwordx4 v[86:87], v[70:73], off
	s_nop 1
	v_lshl_add_u32 v70, v88, 8, v68
	global_load_dwordx4 v[66:69], v[64:65], off
	ds_read_b128 v[70:73], v70
	s_waitcnt vmcnt(0) lgkmcnt(0)
	v_pk_add_f32 v[66:67], v[66:67], v[70:71]
	v_pk_add_f32 v[68:69], v[68:69], v[72:73]
	global_store_dwordx4 v[64:65], v[66:69], off
	v_mov_b32_e32 v64, v148
	s_nop 0
	s_nop 0
	v_and_b32_e32 v65, 31, v64
	v_lshlrev_b32_e32 v66, 5, v64
	v_and_b32_e32 v66, 0xfffffc00, v66
	v_lshlrev_b32_e32 v65, 2, v65
	v_add3_u32 v65, v162, v66, v65
	ds_write2_b32 v65, v48, v32 offset1:32
	ds_write2_b32 v65, v49, v33 offset0:64 offset1:96
	ds_write2_b32 v65, v50, v34 offset0:128 offset1:160
	ds_write2_b32 v65, v51, v35 offset0:192 offset1:224
	v_add_u32_e32 v32, 0x800, v65
	ds_write2_b32 v32, v52, v36 offset1:32
	ds_write2_b32 v32, v53, v37 offset0:64 offset1:96
	ds_write2_b32 v32, v54, v38 offset0:128 offset1:160
	ds_write2_b32 v32, v55, v39 offset0:192 offset1:224
	v_add_u32_e32 v32, 0x1000, v65
	ds_write2_b32 v32, v56, v40 offset1:32
	ds_write2_b32 v32, v57, v41 offset0:64 offset1:96
	ds_write2_b32 v32, v58, v42 offset0:128 offset1:160
	ds_write2_b32 v32, v59, v43 offset0:192 offset1:224
	v_add_u32_e32 v32, 0x1800, v65
	ds_write2_b32 v32, v60, v44 offset1:32
	ds_write2_b32 v32, v61, v45 offset0:64 offset1:96
	ds_write2_b32 v32, v62, v46 offset0:128 offset1:160
	ds_write2_b32 v32, v63, v47 offset0:192 offset1:224
	v_add_u32_e32 v32, 0x2000, v65
	ds_write2_b32 v32, v16, v0 offset1:32
	ds_write2_b32 v32, v17, v1 offset0:64 offset1:96
	ds_write2_b32 v32, v18, v2 offset0:128 offset1:160
	ds_write2_b32 v32, v19, v3 offset0:192 offset1:224
	v_add_u32_e32 v0, 0x2800, v65
	ds_write2_b32 v0, v20, v4 offset1:32
	ds_write2_b32 v0, v21, v5 offset0:64 offset1:96
	ds_write2_b32 v0, v22, v6 offset0:128 offset1:160
	ds_write2_b32 v0, v23, v7 offset0:192 offset1:224
	v_add_u32_e32 v0, 0x3000, v65
	ds_write2_b32 v0, v24, v8 offset1:32
	ds_write2_b32 v0, v25, v9 offset0:64 offset1:96
	ds_write2_b32 v0, v26, v10 offset0:128 offset1:160
	ds_write2_b32 v0, v27, v11 offset0:192 offset1:224
	v_add_u32_e32 v0, 0x3800, v65
	ds_write2_b32 v0, v28, v12 offset1:32
	ds_write2_b32 v0, v29, v13 offset0:64 offset1:96
	ds_write2_b32 v0, v30, v14 offset0:128 offset1:160
	ds_write2_b32 v0, v31, v15 offset0:192 offset1:224
	v_ashrrev_i32_e32 v0, 4, v64
	v_lshlrev_b32_e32 v1, 4, v64
	v_and_b32_e32 v128, 0xf0, v1
	v_ashrrev_i32_e32 v1, 31, v0
	v_add_u32_e32 v16, 4, v0
	v_lshl_add_u64 v[2:3], v[140:141], 0, v[128:129]
	v_lshlrev_b64 v[6:7], 12, v[0:1]
	v_ashrrev_i32_e32 v17, 31, v16
	v_add_u32_e32 v20, 8, v0
	v_lshl_add_u64 v[14:15], v[2:3], 0, v[6:7]
	v_lshlrev_b64 v[6:7], 12, v[16:17]
	v_ashrrev_i32_e32 v21, 31, v20
	v_add_u32_e32 v24, 12, v0
	v_lshl_add_u64 v[18:19], v[2:3], 0, v[6:7]
	v_lshlrev_b64 v[6:7], 12, v[20:21]
	v_ashrrev_i32_e32 v25, 31, v24
	v_lshl_add_u64 v[22:23], v[2:3], 0, v[6:7]
	v_lshlrev_b64 v[6:7], 12, v[24:25]
	v_lshl_add_u64 v[26:27], v[2:3], 0, v[6:7]
	global_load_dwordx4 v[6:9], v[14:15], off offset:256
	v_add_u32_e32 v4, v162, v128
	v_lshl_add_u32 v1, v0, 8, v4
	ds_read_b128 v[10:13], v1
	v_lshl_add_u32 v1, v16, 8, v4
	v_add_u32_e32 v16, 20, v0
	v_ashrrev_i32_e32 v17, 31, v16
	s_waitcnt vmcnt(0) lgkmcnt(0)
	v_pk_add_f32 v[6:7], v[6:7], v[10:11]
	v_pk_add_f32 v[8:9], v[8:9], v[12:13]
	global_store_dwordx4 v[14:15], v[6:9], off offset:256
	global_load_dwordx4 v[6:9], v[18:19], off offset:256
	ds_read_b128 v[10:13], v1
	v_lshl_add_u32 v1, v20, 8, v4
	v_add_u32_e32 v20, 24, v0
	v_ashrrev_i32_e32 v21, 31, v20
	s_waitcnt vmcnt(0) lgkmcnt(0)
	v_pk_add_f32 v[6:7], v[6:7], v[10:11]
	v_pk_add_f32 v[8:9], v[8:9], v[12:13]
	global_store_dwordx4 v[18:19], v[6:9], off offset:256
	global_load_dwordx4 v[6:9], v[22:23], off offset:256
	ds_read_b128 v[10:13], v1
	v_lshl_add_u32 v1, v24, 8, v4
	v_add_u32_e32 v24, 28, v0
	v_ashrrev_i32_e32 v25, 31, v24
	s_waitcnt vmcnt(0) lgkmcnt(0)
	v_pk_add_f32 v[6:7], v[6:7], v[10:11]
	v_pk_add_f32 v[8:9], v[8:9], v[12:13]
	global_store_dwordx4 v[22:23], v[6:9], off offset:256
	global_load_dwordx4 v[6:9], v[26:27], off offset:256
	ds_read_b128 v[10:13], v1
	s_waitcnt vmcnt(0) lgkmcnt(0)
	v_pk_add_f32 v[6:7], v[6:7], v[10:11]
	v_pk_add_f32 v[8:9], v[8:9], v[12:13]
	global_store_dwordx4 v[26:27], v[6:9], off offset:256
	s_nop 1
	v_add_u32_e32 v6, 16, v0
	v_ashrrev_i32_e32 v7, 31, v6
	v_lshlrev_b64 v[8:9], 12, v[6:7]
	v_lshl_add_u64 v[14:15], v[2:3], 0, v[8:9]
	v_lshlrev_b64 v[8:9], 12, v[16:17]
	v_lshl_add_u64 v[18:19], v[2:3], 0, v[8:9]
	v_lshlrev_b64 v[8:9], 12, v[20:21]
	v_lshl_add_u64 v[22:23], v[2:3], 0, v[8:9]
	v_lshlrev_b64 v[8:9], 12, v[24:25]
	v_lshl_add_u64 v[26:27], v[2:3], 0, v[8:9]
	v_lshl_add_u32 v1, v6, 8, v4
	global_load_dwordx4 v[6:9], v[14:15], off offset:256
	ds_read_b128 v[10:13], v1
	v_lshl_add_u32 v1, v16, 8, v4
	v_add_u32_e32 v16, 36, v0
	v_ashrrev_i32_e32 v17, 31, v16
	s_waitcnt vmcnt(0) lgkmcnt(0)
	v_pk_add_f32 v[6:7], v[6:7], v[10:11]
	v_pk_add_f32 v[8:9], v[8:9], v[12:13]
	global_store_dwordx4 v[14:15], v[6:9], off offset:256
	global_load_dwordx4 v[6:9], v[18:19], off offset:256
	ds_read_b128 v[10:13], v1
	v_lshl_add_u32 v1, v20, 8, v4
	v_add_u32_e32 v20, 40, v0
	v_ashrrev_i32_e32 v21, 31, v20
	s_waitcnt vmcnt(0) lgkmcnt(0)
	v_pk_add_f32 v[6:7], v[6:7], v[10:11]
	v_pk_add_f32 v[8:9], v[8:9], v[12:13]
	global_store_dwordx4 v[18:19], v[6:9], off offset:256
	global_load_dwordx4 v[6:9], v[22:23], off offset:256
	ds_read_b128 v[10:13], v1
	v_lshl_add_u32 v1, v24, 8, v4
	v_add_u32_e32 v24, 44, v0
	v_ashrrev_i32_e32 v25, 31, v24
	s_waitcnt vmcnt(0) lgkmcnt(0)
	v_pk_add_f32 v[6:7], v[6:7], v[10:11]
	v_pk_add_f32 v[8:9], v[8:9], v[12:13]
	global_store_dwordx4 v[22:23], v[6:9], off offset:256
	global_load_dwordx4 v[6:9], v[26:27], off offset:256
	ds_read_b128 v[10:13], v1
	s_waitcnt vmcnt(0) lgkmcnt(0)
	v_pk_add_f32 v[6:7], v[6:7], v[10:11]
	v_pk_add_f32 v[8:9], v[8:9], v[12:13]
	global_store_dwordx4 v[26:27], v[6:9], off offset:256
	s_nop 1
	v_add_u32_e32 v6, 32, v0
	v_ashrrev_i32_e32 v7, 31, v6
	v_lshlrev_b64 v[8:9], 12, v[6:7]
	v_lshl_add_u64 v[14:15], v[2:3], 0, v[8:9]
	v_lshlrev_b64 v[8:9], 12, v[16:17]
	v_lshl_add_u64 v[18:19], v[2:3], 0, v[8:9]
	v_lshlrev_b64 v[8:9], 12, v[20:21]
	v_lshl_add_u64 v[22:23], v[2:3], 0, v[8:9]
	v_lshlrev_b64 v[8:9], 12, v[24:25]
	v_lshl_add_u64 v[26:27], v[2:3], 0, v[8:9]
	v_lshl_add_u32 v1, v6, 8, v4
	global_load_dwordx4 v[6:9], v[14:15], off offset:256
	ds_read_b128 v[10:13], v1
	v_lshl_add_u32 v1, v16, 8, v4
	v_add_u32_e32 v16, 52, v0
	v_ashrrev_i32_e32 v17, 31, v16
	s_waitcnt vmcnt(0) lgkmcnt(0)
	v_pk_add_f32 v[6:7], v[6:7], v[10:11]
	v_pk_add_f32 v[8:9], v[8:9], v[12:13]
	global_store_dwordx4 v[14:15], v[6:9], off offset:256
	global_load_dwordx4 v[6:9], v[18:19], off offset:256
	ds_read_b128 v[10:13], v1
	v_lshl_add_u32 v1, v20, 8, v4
	v_add_u32_e32 v20, 56, v0
	v_ashrrev_i32_e32 v21, 31, v20
	s_waitcnt vmcnt(0) lgkmcnt(0)
	v_pk_add_f32 v[6:7], v[6:7], v[10:11]
	v_pk_add_f32 v[8:9], v[8:9], v[12:13]
	global_store_dwordx4 v[18:19], v[6:9], off offset:256
	global_load_dwordx4 v[6:9], v[22:23], off offset:256
	ds_read_b128 v[10:13], v1
	v_lshl_add_u32 v1, v24, 8, v4
	v_add_u32_e32 v24, 60, v0
	v_ashrrev_i32_e32 v25, 31, v24
	s_waitcnt vmcnt(0) lgkmcnt(0)
	v_pk_add_f32 v[6:7], v[6:7], v[10:11]
	v_pk_add_f32 v[8:9], v[8:9], v[12:13]
	global_store_dwordx4 v[22:23], v[6:9], off offset:256
	global_load_dwordx4 v[6:9], v[26:27], off offset:256
	ds_read_b128 v[10:13], v1
	s_waitcnt vmcnt(0) lgkmcnt(0)
	v_pk_add_f32 v[6:7], v[6:7], v[10:11]
	v_pk_add_f32 v[8:9], v[8:9], v[12:13]
	global_store_dwordx4 v[26:27], v[6:9], off offset:256
	s_nop 1
	v_add_u32_e32 v6, 48, v0
	v_ashrrev_i32_e32 v7, 31, v6
	v_lshlrev_b64 v[8:9], 12, v[6:7]
	v_lshl_add_u64 v[14:15], v[2:3], 0, v[8:9]
	v_lshlrev_b64 v[8:9], 12, v[16:17]
	v_lshl_add_u64 v[18:19], v[2:3], 0, v[8:9]
	v_lshlrev_b64 v[8:9], 12, v[20:21]
	v_lshlrev_b64 v[0:1], 12, v[24:25]
	v_lshl_add_u64 v[22:23], v[2:3], 0, v[8:9]
	v_lshl_add_u64 v[0:1], v[2:3], 0, v[0:1]
	v_lshl_add_u32 v2, v6, 8, v4
	global_load_dwordx4 v[6:9], v[14:15], off offset:256
	ds_read_b128 v[10:13], v2
	v_lshl_add_u32 v2, v16, 8, v4
	s_waitcnt vmcnt(0) lgkmcnt(0)
	v_pk_add_f32 v[6:7], v[6:7], v[10:11]
	v_pk_add_f32 v[8:9], v[8:9], v[12:13]
	global_store_dwordx4 v[14:15], v[6:9], off offset:256
	global_load_dwordx4 v[6:9], v[18:19], off offset:256
	ds_read_b128 v[10:13], v2
	v_lshl_add_u32 v2, v20, 8, v4
	s_waitcnt vmcnt(0) lgkmcnt(0)
	v_pk_add_f32 v[6:7], v[6:7], v[10:11]
	v_pk_add_f32 v[8:9], v[8:9], v[12:13]
	global_store_dwordx4 v[18:19], v[6:9], off offset:256
	global_load_dwordx4 v[6:9], v[22:23], off offset:256
	ds_read_b128 v[10:13], v2
	s_waitcnt vmcnt(0) lgkmcnt(0)
	v_pk_add_f32 v[6:7], v[6:7], v[10:11]
	v_pk_add_f32 v[8:9], v[8:9], v[12:13]
	global_store_dwordx4 v[22:23], v[6:9], off offset:256
	s_nop 1
	v_lshl_add_u32 v6, v24, 8, v4
	global_load_dwordx4 v[2:5], v[0:1], off offset:256
	ds_read_b128 v[6:9], v6
	s_waitcnt vmcnt(0) lgkmcnt(0)
	v_pk_add_f32 v[2:3], v[2:3], v[6:7]
	v_pk_add_f32 v[4:5], v[4:5], v[8:9]
	global_store_dwordx4 v[0:1], v[2:5], off offset:256
	s_cbranch_scc0 .LBB0_1047
